# GEMM tiles (6 instances): first K iteration peeled with C=0 MFMAs, accumulator zeroing removed from the tile prologue; on top of v48
# speedup vs baseline: 1.0061x; 1.0029x over previous
.LBB0_725:
	s_andn2_b64 vcc, exec, s[12:13]
	s_cbranch_vccnz .Lpz_zero_1
	s_add_u32 s30, s4, 0x10080
	s_addc_u32 s31, s5, 0
	s_add_u32 s23, s34, 0x100
	s_addc_u32 s25, s35, 0
	s_mov_b32 s4, 0
	ds_read_b128 v[144:147], v141
	ds_read_b128 v[150:153], v141 offset:1024
	ds_read_b128 v[154:157], v141 offset:2048
	ds_read_b128 v[158:161], v141 offset:3072
	ds_read_b128 v[162:165], v142
	ds_read_b128 v[166:169], v142 offset:1024
	ds_read_b128 v[170:173], v142 offset:2048
	ds_read_b128 v[174:177], v142 offset:3072
	s_add_i32 s54, s4, 2
	s_add_u32 s5, s30, 0xffff0080
	s_addc_u32 s34, s31, -1
	s_cmp_eq_u32 s46, s4
	s_cselect_b32 s4, s28, s23
	s_cselect_b32 s35, s27, s34
	s_cselect_b32 s34, s26, s5
	s_cselect_b32 s5, s29, s25
	v_lshl_add_u64 v[186:187], s[30:31], 0, v[132:133]
	s_add_i32 m0, s17, 0xc000
	ds_read_b128 v[178:181], v143
	ds_read_b128 v[182:185], v143 offset:1024
	ds_read_b128 v[190:193], v143 offset:2048
	ds_read_b128 v[194:197], v143 offset:3072
	ds_read_b128 v[198:201], v143 offset:4096
	ds_read_b128 v[202:205], v143 offset:5120
	ds_read_b128 v[206:209], v143 offset:6144
	ds_read_b128 v[210:213], v143 offset:7168
	global_load_lds_dwordx4 v[186:187], off
	v_lshl_add_u64 v[186:187], s[30:31], 0, v[134:135]
	s_add_i32 m0, s17, 0xe000
	s_nop 0
	global_load_lds_dwordx4 v[186:187], off
	s_waitcnt vmcnt(8)
	s_waitcnt lgkmcnt(0)
	s_barrier
	s_setprio 1
	s_waitcnt lgkmcnt(0)
	v_mfma_f32_16x16x32_bf16 v[120:123], v[144:147], v[178:181], 0
	v_mfma_f32_16x16x32_bf16 v[124:127], v[154:157], v[178:181], 0
	v_mfma_f32_16x16x32_bf16 v[108:111], v[144:147], v[190:193], 0
	v_mfma_f32_16x16x32_bf16 v[104:107], v[154:157], v[190:193], 0
	v_mfma_f32_16x16x32_bf16 v[92:95], v[144:147], v[198:201], 0
	v_mfma_f32_16x16x32_bf16 v[88:91], v[154:157], v[198:201], 0
	v_mfma_f32_16x16x32_bf16 v[76:79], v[144:147], v[206:209], 0
	v_mfma_f32_16x16x32_bf16 v[72:75], v[154:157], v[206:209], 0
	v_mfma_f32_16x16x32_bf16 v[120:123], v[150:153], v[182:185], v[120:123]
	v_mfma_f32_16x16x32_bf16 v[124:127], v[158:161], v[182:185], v[124:127]
	v_mfma_f32_16x16x32_bf16 v[108:111], v[150:153], v[194:197], v[108:111]
	v_mfma_f32_16x16x32_bf16 v[104:107], v[158:161], v[194:197], v[104:107]
	v_mfma_f32_16x16x32_bf16 v[92:95], v[150:153], v[202:205], v[92:95]
	v_mfma_f32_16x16x32_bf16 v[88:91], v[158:161], v[202:205], v[88:91]
	v_mfma_f32_16x16x32_bf16 v[76:79], v[150:153], v[210:213], v[76:79]
	v_mfma_f32_16x16x32_bf16 v[72:75], v[158:161], v[210:213], v[72:75]
	s_setprio 0
	s_setprio 1
	v_mfma_f32_16x16x32_bf16 v[116:119], v[162:165], v[178:181], 0
	v_mfma_f32_16x16x32_bf16 v[112:115], v[170:173], v[178:181], 0
	v_mfma_f32_16x16x32_bf16 v[100:103], v[162:165], v[190:193], 0
	v_mfma_f32_16x16x32_bf16 v[96:99], v[170:173], v[190:193], 0
	v_mfma_f32_16x16x32_bf16 v[84:87], v[162:165], v[198:201], 0
	v_mfma_f32_16x16x32_bf16 v[80:83], v[170:173], v[198:201], 0
	v_mfma_f32_16x16x32_bf16 v[68:71], v[162:165], v[206:209], 0
	v_mfma_f32_16x16x32_bf16 v[64:67], v[170:173], v[206:209], 0
	v_mfma_f32_16x16x32_bf16 v[116:119], v[166:169], v[182:185], v[116:119]
	v_mfma_f32_16x16x32_bf16 v[112:115], v[174:177], v[182:185], v[112:115]
	v_mfma_f32_16x16x32_bf16 v[100:103], v[166:169], v[194:197], v[100:103]
	v_mfma_f32_16x16x32_bf16 v[96:99], v[174:177], v[194:197], v[96:99]
	v_mfma_f32_16x16x32_bf16 v[84:87], v[166:169], v[202:205], v[84:87]
	v_mfma_f32_16x16x32_bf16 v[80:83], v[174:177], v[202:205], v[80:83]
	v_mfma_f32_16x16x32_bf16 v[68:71], v[166:169], v[210:213], v[68:71]
	v_mfma_f32_16x16x32_bf16 v[64:67], v[174:177], v[210:213], v[64:67]
	s_setprio 0
	s_barrier
	s_add_i32 s55, s51, s33
	v_lshl_add_u64 v[186:187], s[4:5], 0, v[128:129]
	s_mov_b32 m0, s55
	ds_read_b128 v[178:181], v143 offset:16384
	ds_read_b128 v[182:185], v143 offset:17408
	ds_read_b128 v[190:193], v143 offset:18432
	ds_read_b128 v[194:197], v143 offset:19456
	ds_read_b128 v[198:201], v143 offset:20480
	ds_read_b128 v[202:205], v143 offset:21504
	ds_read_b128 v[206:209], v143 offset:22528
	ds_read_b128 v[210:213], v143 offset:23552
	global_load_lds_dwordx4 v[186:187], off
	s_add_i32 m0, s55, 0x2000
	s_add_u32 s56, s4, 0x10000
	v_lshl_add_u64 v[214:215], s[4:5], 0, v[130:131]
	s_addc_u32 s57, s5, 0
	s_add_i32 s55, s52, s33
	global_load_lds_dwordx4 v[214:215], off
	v_lshl_add_u64 v[216:217], s[56:57], 0, v[128:129]
	s_mov_b32 m0, s55
	v_lshl_add_u64 v[218:219], s[34:35], 0, v[130:131]
	global_load_lds_dwordx4 v[216:217], off
	v_lshl_add_u64 v[216:217], s[56:57], 0, v[130:131]
	s_add_i32 m0, s55, 0x2000
	s_nop 0
	global_load_lds_dwordx4 v[216:217], off
	v_lshl_add_u64 v[216:217], s[34:35], 0, v[128:129]
	s_mov_b32 m0, s17
	s_nop 0
	global_load_lds_dwordx4 v[216:217], off
	s_mov_b32 m0, s21
	s_nop 0
	global_load_lds_dwordx4 v[218:219], off
	s_waitcnt vmcnt(8)
	s_waitcnt lgkmcnt(0)
	s_barrier
	s_setprio 1
	s_waitcnt lgkmcnt(0)
	v_mfma_f32_16x16x32_bf16 v[60:63], v[144:147], v[178:181], 0
	v_mfma_f32_16x16x32_bf16 v[56:59], v[154:157], v[178:181], 0
	v_mfma_f32_16x16x32_bf16 v[44:47], v[144:147], v[190:193], 0
	v_mfma_f32_16x16x32_bf16 v[40:43], v[154:157], v[190:193], 0
	v_mfma_f32_16x16x32_bf16 v[28:31], v[144:147], v[198:201], 0
	v_mfma_f32_16x16x32_bf16 v[24:27], v[154:157], v[198:201], 0
	v_mfma_f32_16x16x32_bf16 v[12:15], v[144:147], v[206:209], 0
	v_mfma_f32_16x16x32_bf16 v[8:11], v[154:157], v[206:209], 0
	v_mfma_f32_16x16x32_bf16 v[60:63], v[150:153], v[182:185], v[60:63]
	v_mfma_f32_16x16x32_bf16 v[56:59], v[158:161], v[182:185], v[56:59]
	v_mfma_f32_16x16x32_bf16 v[44:47], v[150:153], v[194:197], v[44:47]
	v_mfma_f32_16x16x32_bf16 v[40:43], v[158:161], v[194:197], v[40:43]
	v_mfma_f32_16x16x32_bf16 v[28:31], v[150:153], v[202:205], v[28:31]
	v_mfma_f32_16x16x32_bf16 v[24:27], v[158:161], v[202:205], v[24:27]
	v_mfma_f32_16x16x32_bf16 v[12:15], v[150:153], v[210:213], v[12:15]
	v_mfma_f32_16x16x32_bf16 v[8:11], v[158:161], v[210:213], v[8:11]
	s_setprio 0
	s_setprio 1
	v_mfma_f32_16x16x32_bf16 v[52:55], v[162:165], v[178:181], 0
	v_mfma_f32_16x16x32_bf16 v[48:51], v[170:173], v[178:181], 0
	v_mfma_f32_16x16x32_bf16 v[36:39], v[162:165], v[190:193], 0
	v_mfma_f32_16x16x32_bf16 v[32:35], v[170:173], v[190:193], 0
	v_mfma_f32_16x16x32_bf16 v[20:23], v[162:165], v[198:201], 0
	v_mfma_f32_16x16x32_bf16 v[16:19], v[170:173], v[198:201], 0
	v_mfma_f32_16x16x32_bf16 v[4:7], v[162:165], v[206:209], 0
	v_mfma_f32_16x16x32_bf16 v[0:3], v[170:173], v[206:209], 0
	v_mfma_f32_16x16x32_bf16 v[52:55], v[166:169], v[182:185], v[52:55]
	v_mfma_f32_16x16x32_bf16 v[48:51], v[174:177], v[182:185], v[48:51]
	v_mfma_f32_16x16x32_bf16 v[36:39], v[166:169], v[194:197], v[36:39]
	v_mfma_f32_16x16x32_bf16 v[32:35], v[174:177], v[194:197], v[32:35]
	v_mfma_f32_16x16x32_bf16 v[20:23], v[166:169], v[202:205], v[20:23]
	v_mfma_f32_16x16x32_bf16 v[16:19], v[174:177], v[202:205], v[16:19]
	v_mfma_f32_16x16x32_bf16 v[4:7], v[166:169], v[210:213], v[4:7]
	v_mfma_f32_16x16x32_bf16 v[0:3], v[174:177], v[210:213], v[0:3]
	s_setprio 0
	s_barrier
	s_add_i32 s55, 0, 0x18000
	v_add_u32_e32 v149, s55, v139
	s_add_i32 s56, 0, 0x1c000
	ds_read_b128 v[144:147], v149
	ds_read_b128 v[150:153], v149 offset:1024
	ds_read_b128 v[154:157], v149 offset:2048
	ds_read_b128 v[158:161], v149 offset:3072
	v_add_u32_e32 v149, s56, v139
	ds_read_b128 v[162:165], v149
	ds_read_b128 v[166:169], v149 offset:1024
	ds_read_b128 v[170:173], v149 offset:2048
	ds_read_b128 v[174:177], v149 offset:3072
	s_add_u32 s34, s34, 0x10000
	s_addc_u32 s35, s35, 0
	s_mov_b32 m0, s40
	v_lshl_add_u64 v[220:221], s[34:35], 0, v[128:129]
	ds_read_b128 v[178:181], v143 offset:32768
	ds_read_b128 v[182:185], v143 offset:33792
	ds_read_b128 v[190:193], v143 offset:34816
	ds_read_b128 v[194:197], v143 offset:35840
	ds_read_b128 v[198:201], v143 offset:36864
	ds_read_b128 v[202:205], v143 offset:37888
	ds_read_b128 v[206:209], v143 offset:38912
	ds_read_b128 v[210:213], v143 offset:39936
	global_load_lds_dwordx4 v[220:221], off
	v_lshl_add_u64 v[220:221], s[34:35], 0, v[130:131]
	s_mov_b32 m0, s41
	s_nop 0
	global_load_lds_dwordx4 v[220:221], off
	s_waitcnt vmcnt(8)
	s_waitcnt lgkmcnt(0)
	s_barrier
	s_setprio 1
	s_waitcnt lgkmcnt(0)
	v_mfma_f32_16x16x32_bf16 v[120:123], v[144:147], v[178:181], v[120:123]
	v_mfma_f32_16x16x32_bf16 v[124:127], v[154:157], v[178:181], v[124:127]
	v_mfma_f32_16x16x32_bf16 v[108:111], v[144:147], v[190:193], v[108:111]
	v_mfma_f32_16x16x32_bf16 v[104:107], v[154:157], v[190:193], v[104:107]
	v_mfma_f32_16x16x32_bf16 v[92:95], v[144:147], v[198:201], v[92:95]
	v_mfma_f32_16x16x32_bf16 v[88:91], v[154:157], v[198:201], v[88:91]
	v_mfma_f32_16x16x32_bf16 v[76:79], v[144:147], v[206:209], v[76:79]
	v_mfma_f32_16x16x32_bf16 v[72:75], v[154:157], v[206:209], v[72:75]
	v_mfma_f32_16x16x32_bf16 v[120:123], v[150:153], v[182:185], v[120:123]
	v_mfma_f32_16x16x32_bf16 v[124:127], v[158:161], v[182:185], v[124:127]
	v_mfma_f32_16x16x32_bf16 v[108:111], v[150:153], v[194:197], v[108:111]
	v_mfma_f32_16x16x32_bf16 v[104:107], v[158:161], v[194:197], v[104:107]
	v_mfma_f32_16x16x32_bf16 v[92:95], v[150:153], v[202:205], v[92:95]
	v_mfma_f32_16x16x32_bf16 v[88:91], v[158:161], v[202:205], v[88:91]
	v_mfma_f32_16x16x32_bf16 v[76:79], v[150:153], v[210:213], v[76:79]
	v_mfma_f32_16x16x32_bf16 v[72:75], v[158:161], v[210:213], v[72:75]
	s_setprio 0
	s_setprio 1
	v_mfma_f32_16x16x32_bf16 v[116:119], v[162:165], v[178:181], v[116:119]
	v_mfma_f32_16x16x32_bf16 v[112:115], v[170:173], v[178:181], v[112:115]
	v_mfma_f32_16x16x32_bf16 v[100:103], v[162:165], v[190:193], v[100:103]
	v_mfma_f32_16x16x32_bf16 v[96:99], v[170:173], v[190:193], v[96:99]
	v_mfma_f32_16x16x32_bf16 v[84:87], v[162:165], v[198:201], v[84:87]
	v_mfma_f32_16x16x32_bf16 v[80:83], v[170:173], v[198:201], v[80:83]
	v_mfma_f32_16x16x32_bf16 v[68:71], v[162:165], v[206:209], v[68:71]
	v_mfma_f32_16x16x32_bf16 v[64:67], v[170:173], v[206:209], v[64:67]
	v_mfma_f32_16x16x32_bf16 v[116:119], v[166:169], v[182:185], v[116:119]
	v_mfma_f32_16x16x32_bf16 v[112:115], v[174:177], v[182:185], v[112:115]
	v_mfma_f32_16x16x32_bf16 v[100:103], v[166:169], v[194:197], v[100:103]
	v_mfma_f32_16x16x32_bf16 v[96:99], v[174:177], v[194:197], v[96:99]
	v_mfma_f32_16x16x32_bf16 v[84:87], v[166:169], v[202:205], v[84:87]
	v_mfma_f32_16x16x32_bf16 v[80:83], v[174:177], v[202:205], v[80:83]
	v_mfma_f32_16x16x32_bf16 v[68:71], v[166:169], v[210:213], v[68:71]
	v_mfma_f32_16x16x32_bf16 v[64:67], v[174:177], v[210:213], v[64:67]
	s_setprio 0
	s_barrier
	s_add_i32 s34, s55, s33
	v_lshl_add_u64 v[186:187], v[186:187], 0, s[10:11]
	s_mov_b32 m0, s34
	ds_read_b128 v[178:181], v143 offset:49152
	ds_read_b128 v[182:185], v143 offset:50176
	ds_read_b128 v[190:193], v143 offset:51200
	ds_read_b128 v[194:197], v143 offset:52224
	ds_read_b128 v[198:201], v143 offset:53248
	ds_read_b128 v[202:205], v143 offset:54272
	ds_read_b128 v[206:209], v143 offset:55296
	ds_read_b128 v[210:213], v143 offset:56320
	global_load_lds_dwordx4 v[186:187], off
	s_add_i32 m0, s34, 0x2000
	s_add_u32 s4, s4, 0x10080
	v_lshl_add_u64 v[186:187], v[214:215], 0, s[10:11]
	s_addc_u32 s5, s5, 0
	s_add_i32 s34, s56, s33
	global_load_lds_dwordx4 v[186:187], off
	v_lshl_add_u64 v[186:187], s[4:5], 0, v[128:129]
	s_mov_b32 m0, s34
	s_nop 0
	global_load_lds_dwordx4 v[186:187], off
	v_lshl_add_u64 v[186:187], s[4:5], 0, v[130:131]
	s_add_i32 m0, s34, 0x2000
	s_nop 0
	global_load_lds_dwordx4 v[186:187], off
	v_lshl_add_u64 v[186:187], v[216:217], 0, s[10:11]
	s_mov_b32 m0, s44
	s_nop 0
	global_load_lds_dwordx4 v[186:187], off
	v_lshl_add_u64 v[186:187], v[218:219], 0, s[10:11]
	s_mov_b32 m0, s45
	s_nop 0
	global_load_lds_dwordx4 v[186:187], off
	s_waitcnt vmcnt(8)
	s_waitcnt lgkmcnt(0)
	s_barrier
	s_setprio 1
	s_waitcnt lgkmcnt(0)
	v_mfma_f32_16x16x32_bf16 v[60:63], v[144:147], v[178:181], v[60:63]
	v_mfma_f32_16x16x32_bf16 v[56:59], v[154:157], v[178:181], v[56:59]
	v_mfma_f32_16x16x32_bf16 v[44:47], v[144:147], v[190:193], v[44:47]
	v_mfma_f32_16x16x32_bf16 v[40:43], v[154:157], v[190:193], v[40:43]
	v_mfma_f32_16x16x32_bf16 v[28:31], v[144:147], v[198:201], v[28:31]
	v_mfma_f32_16x16x32_bf16 v[24:27], v[154:157], v[198:201], v[24:27]
	v_mfma_f32_16x16x32_bf16 v[12:15], v[144:147], v[206:209], v[12:15]
	v_mfma_f32_16x16x32_bf16 v[8:11], v[154:157], v[206:209], v[8:11]
	v_mfma_f32_16x16x32_bf16 v[60:63], v[150:153], v[182:185], v[60:63]
	v_mfma_f32_16x16x32_bf16 v[56:59], v[158:161], v[182:185], v[56:59]
	v_mfma_f32_16x16x32_bf16 v[44:47], v[150:153], v[194:197], v[44:47]
	v_mfma_f32_16x16x32_bf16 v[40:43], v[158:161], v[194:197], v[40:43]
	v_mfma_f32_16x16x32_bf16 v[28:31], v[150:153], v[202:205], v[28:31]
	v_mfma_f32_16x16x32_bf16 v[24:27], v[158:161], v[202:205], v[24:27]
	v_mfma_f32_16x16x32_bf16 v[12:15], v[150:153], v[210:213], v[12:15]
	v_mfma_f32_16x16x32_bf16 v[8:11], v[158:161], v[210:213], v[8:11]
	s_setprio 0
	s_setprio 1
	v_mfma_f32_16x16x32_bf16 v[52:55], v[162:165], v[178:181], v[52:55]
	v_mfma_f32_16x16x32_bf16 v[48:51], v[170:173], v[178:181], v[48:51]
	v_mfma_f32_16x16x32_bf16 v[36:39], v[162:165], v[190:193], v[36:39]
	v_mfma_f32_16x16x32_bf16 v[32:35], v[170:173], v[190:193], v[32:35]
	v_mfma_f32_16x16x32_bf16 v[20:23], v[162:165], v[198:201], v[20:23]
	v_mfma_f32_16x16x32_bf16 v[16:19], v[170:173], v[198:201], v[16:19]
	v_mfma_f32_16x16x32_bf16 v[4:7], v[162:165], v[206:209], v[4:7]
	v_mfma_f32_16x16x32_bf16 v[0:3], v[170:173], v[206:209], v[0:3]
	v_mfma_f32_16x16x32_bf16 v[52:55], v[166:169], v[182:185], v[52:55]
	v_mfma_f32_16x16x32_bf16 v[48:51], v[174:177], v[182:185], v[48:51]
	v_mfma_f32_16x16x32_bf16 v[36:39], v[166:169], v[194:197], v[36:39]
	v_mfma_f32_16x16x32_bf16 v[32:35], v[174:177], v[194:197], v[32:35]
	v_mfma_f32_16x16x32_bf16 v[20:23], v[166:169], v[202:205], v[20:23]
	v_mfma_f32_16x16x32_bf16 v[16:19], v[174:177], v[202:205], v[16:19]
	v_mfma_f32_16x16x32_bf16 v[4:7], v[166:169], v[210:213], v[4:7]
	v_mfma_f32_16x16x32_bf16 v[0:3], v[174:177], v[210:213], v[0:3]
	s_setprio 0
	s_barrier
	s_add_u32 s30, s30, 0x100
	s_addc_u32 s31, s31, 0
	s_add_u32 s23, s23, 0x100
	s_addc_u32 s25, s25, 0
	s_cmp_ge_i32 s54, s42
	s_mov_b32 s4, s54
	s_cbranch_scc0 .LBB0_727
	s_branch .LBB0_728
.Lpz_zero_1:
	v_mov_b64_e32 v[122:123], 0
	v_mov_b64_e32 v[120:121], 0
	v_mov_b64_e32 v[126:127], 0
	v_mov_b64_e32 v[124:125], 0
	v_mov_b64_e32 v[110:111], 0
	v_mov_b64_e32 v[108:109], 0
	v_mov_b64_e32 v[106:107], 0
	v_mov_b64_e32 v[104:105], 0
	v_mov_b64_e32 v[94:95], 0
	v_mov_b64_e32 v[92:93], 0
	v_mov_b64_e32 v[90:91], 0
	v_mov_b64_e32 v[88:89], 0
	v_mov_b64_e32 v[78:79], 0
	v_mov_b64_e32 v[76:77], 0
	v_mov_b64_e32 v[74:75], 0
	v_mov_b64_e32 v[72:73], 0
	v_mov_b64_e32 v[118:119], 0
	v_mov_b64_e32 v[116:117], 0
	v_mov_b64_e32 v[114:115], 0
	v_mov_b64_e32 v[112:113], 0
	v_mov_b64_e32 v[102:103], 0
	v_mov_b64_e32 v[100:101], 0
	v_mov_b64_e32 v[98:99], 0
	v_mov_b64_e32 v[96:97], 0
	v_mov_b64_e32 v[86:87], 0
	v_mov_b64_e32 v[84:85], 0
	v_mov_b64_e32 v[82:83], 0
	v_mov_b64_e32 v[80:81], 0
	v_mov_b64_e32 v[70:71], 0
	v_mov_b64_e32 v[68:69], 0
	v_mov_b64_e32 v[66:67], 0
	v_mov_b64_e32 v[64:65], 0
	v_mov_b64_e32 v[62:63], 0
	v_mov_b64_e32 v[60:61], 0
	v_mov_b64_e32 v[58:59], 0
	v_mov_b64_e32 v[56:57], 0
	v_mov_b64_e32 v[46:47], 0
	v_mov_b64_e32 v[44:45], 0
	v_mov_b64_e32 v[42:43], 0
	v_mov_b64_e32 v[40:41], 0
	v_mov_b64_e32 v[30:31], 0
	v_mov_b64_e32 v[28:29], 0
	v_mov_b64_e32 v[26:27], 0
	v_mov_b64_e32 v[24:25], 0
	v_mov_b64_e32 v[14:15], 0
	v_mov_b64_e32 v[12:13], 0
	v_mov_b64_e32 v[10:11], 0
	v_mov_b64_e32 v[8:9], 0
	v_mov_b64_e32 v[54:55], 0
	v_mov_b64_e32 v[52:53], 0
	v_mov_b64_e32 v[50:51], 0
	v_mov_b64_e32 v[48:49], 0
	v_mov_b64_e32 v[38:39], 0
	v_mov_b64_e32 v[36:37], 0
	v_mov_b64_e32 v[34:35], 0
	v_mov_b64_e32 v[32:33], 0
	v_mov_b64_e32 v[22:23], 0
	v_mov_b64_e32 v[20:21], 0
	v_mov_b64_e32 v[18:19], 0
	v_mov_b64_e32 v[16:17], 0
	v_mov_b64_e32 v[6:7], 0
	v_mov_b64_e32 v[4:5], 0
	v_mov_b64_e32 v[2:3], 0
	v_mov_b64_e32 v[0:1], 0
	s_branch .LBB0_728

.LBB0_1264:
	s_andn2_b64 vcc, exec, s[14:15]
	s_cbranch_vccnz .Lpz_zero_2
	s_add_u32 s30, s30, 0x20080
	s_addc_u32 s31, s31, 0
	s_add_u32 s21, s4, 0x100
	s_addc_u32 s23, s5, 0
	s_mov_b32 s4, 0
	ds_read_b128 v[138:141], v152
	ds_read_b128 v[142:145], v152 offset:1024
	ds_read_b128 v[156:159], v152 offset:2048
	ds_read_b128 v[160:163], v152 offset:3072
	ds_read_b128 v[164:167], v153
	ds_read_b128 v[168:171], v153 offset:1024
	ds_read_b128 v[172:175], v153 offset:2048
	ds_read_b128 v[176:179], v153 offset:3072
	s_add_i32 s58, s4, 2
	s_add_u32 s5, s30, 0xfffe0080
	s_addc_u32 s34, s31, -1
	s_cmp_eq_u32 s48, s4
	s_cselect_b32 s4, s26, s21
	s_cselect_b32 s35, s25, s34
	s_cselect_b32 s34, s24, s5
	s_cselect_b32 s5, s27, s23
	v_lshl_add_u64 v[214:215], s[30:31], 0, v[132:133]
	s_add_i32 m0, s37, 0xc000
	ds_read_b128 v[180:183], v154
	ds_read_b128 v[184:187], v154 offset:1024
	ds_read_b128 v[190:193], v154 offset:2048
	ds_read_b128 v[194:197], v154 offset:3072
	ds_read_b128 v[198:201], v154 offset:4096
	ds_read_b128 v[202:205], v154 offset:5120
	ds_read_b128 v[206:209], v154 offset:6144
	ds_read_b128 v[210:213], v154 offset:7168
	global_load_lds_dwordx4 v[214:215], off
	v_lshl_add_u64 v[214:215], s[30:31], 0, v[134:135]
	s_add_i32 m0, s37, 0xe000
	s_nop 0
	global_load_lds_dwordx4 v[214:215], off
	s_waitcnt vmcnt(8)
	s_waitcnt lgkmcnt(0)
	s_barrier
	s_setprio 1
	s_waitcnt lgkmcnt(0)
	v_mfma_f32_16x16x32_bf16 v[120:123], v[138:141], v[180:183], 0
	v_mfma_f32_16x16x32_bf16 v[124:127], v[156:159], v[180:183], 0
	v_mfma_f32_16x16x32_bf16 v[108:111], v[138:141], v[190:193], 0
	v_mfma_f32_16x16x32_bf16 v[104:107], v[156:159], v[190:193], 0
	v_mfma_f32_16x16x32_bf16 v[92:95], v[138:141], v[198:201], 0
	v_mfma_f32_16x16x32_bf16 v[88:91], v[156:159], v[198:201], 0
	v_mfma_f32_16x16x32_bf16 v[76:79], v[138:141], v[206:209], 0
	v_mfma_f32_16x16x32_bf16 v[72:75], v[156:159], v[206:209], 0
	v_mfma_f32_16x16x32_bf16 v[120:123], v[142:145], v[184:187], v[120:123]
	v_mfma_f32_16x16x32_bf16 v[124:127], v[160:163], v[184:187], v[124:127]
	v_mfma_f32_16x16x32_bf16 v[108:111], v[142:145], v[194:197], v[108:111]
	v_mfma_f32_16x16x32_bf16 v[104:107], v[160:163], v[194:197], v[104:107]
	v_mfma_f32_16x16x32_bf16 v[92:95], v[142:145], v[202:205], v[92:95]
	v_mfma_f32_16x16x32_bf16 v[88:91], v[160:163], v[202:205], v[88:91]
	v_mfma_f32_16x16x32_bf16 v[76:79], v[142:145], v[210:213], v[76:79]
	v_mfma_f32_16x16x32_bf16 v[72:75], v[160:163], v[210:213], v[72:75]
	s_setprio 0
	s_setprio 1
	v_mfma_f32_16x16x32_bf16 v[116:119], v[164:167], v[180:183], 0
	v_mfma_f32_16x16x32_bf16 v[112:115], v[172:175], v[180:183], 0
	v_mfma_f32_16x16x32_bf16 v[100:103], v[164:167], v[190:193], 0
	v_mfma_f32_16x16x32_bf16 v[96:99], v[172:175], v[190:193], 0
	v_mfma_f32_16x16x32_bf16 v[84:87], v[164:167], v[198:201], 0
	v_mfma_f32_16x16x32_bf16 v[80:83], v[172:175], v[198:201], 0
	v_mfma_f32_16x16x32_bf16 v[68:71], v[164:167], v[206:209], 0
	v_mfma_f32_16x16x32_bf16 v[64:67], v[172:175], v[206:209], 0
	v_mfma_f32_16x16x32_bf16 v[116:119], v[168:171], v[184:187], v[116:119]
	v_mfma_f32_16x16x32_bf16 v[112:115], v[176:179], v[184:187], v[112:115]
	v_mfma_f32_16x16x32_bf16 v[100:103], v[168:171], v[194:197], v[100:103]
	v_mfma_f32_16x16x32_bf16 v[96:99], v[176:179], v[194:197], v[96:99]
	v_mfma_f32_16x16x32_bf16 v[84:87], v[168:171], v[202:205], v[84:87]
	v_mfma_f32_16x16x32_bf16 v[80:83], v[176:179], v[202:205], v[80:83]
	v_mfma_f32_16x16x32_bf16 v[68:71], v[168:171], v[210:213], v[68:71]
	v_mfma_f32_16x16x32_bf16 v[64:67], v[176:179], v[210:213], v[64:67]
	s_setprio 0
	s_barrier
	s_add_i32 s59, s52, s29
	v_lshl_add_u64 v[214:215], s[4:5], 0, v[128:129]
	s_mov_b32 m0, s59
	ds_read_b128 v[180:183], v154 offset:16384
	ds_read_b128 v[184:187], v154 offset:17408
	ds_read_b128 v[190:193], v154 offset:18432
	ds_read_b128 v[194:197], v154 offset:19456
	ds_read_b128 v[198:201], v154 offset:20480
	ds_read_b128 v[202:205], v154 offset:21504
	ds_read_b128 v[206:209], v154 offset:22528
	ds_read_b128 v[210:213], v154 offset:23552
	global_load_lds_dwordx4 v[214:215], off
	s_add_i32 m0, s59, 0x2000
	s_add_u32 s60, s4, 0x20000
	v_lshl_add_u64 v[216:217], s[4:5], 0, v[130:131]
	s_addc_u32 s61, s5, 0
	s_add_i32 s59, s53, s29
	global_load_lds_dwordx4 v[216:217], off
	v_lshl_add_u64 v[218:219], s[60:61], 0, v[128:129]
	s_mov_b32 m0, s59
	v_lshl_add_u64 v[220:221], s[34:35], 0, v[130:131]
	global_load_lds_dwordx4 v[218:219], off
	v_lshl_add_u64 v[218:219], s[60:61], 0, v[130:131]
	s_add_i32 m0, s59, 0x2000
	s_nop 0
	global_load_lds_dwordx4 v[218:219], off
	v_lshl_add_u64 v[218:219], s[34:35], 0, v[128:129]
	s_mov_b32 m0, s37
	s_nop 0
	global_load_lds_dwordx4 v[218:219], off
	s_mov_b32 m0, s38
	s_nop 0
	global_load_lds_dwordx4 v[220:221], off
	s_waitcnt vmcnt(8)
	s_waitcnt lgkmcnt(0)
	s_barrier
	s_setprio 1
	s_waitcnt lgkmcnt(0)
	v_mfma_f32_16x16x32_bf16 v[60:63], v[138:141], v[180:183], 0
	v_mfma_f32_16x16x32_bf16 v[56:59], v[156:159], v[180:183], 0
	v_mfma_f32_16x16x32_bf16 v[44:47], v[138:141], v[190:193], 0
	v_mfma_f32_16x16x32_bf16 v[40:43], v[156:159], v[190:193], 0
	v_mfma_f32_16x16x32_bf16 v[28:31], v[138:141], v[198:201], 0
	v_mfma_f32_16x16x32_bf16 v[24:27], v[156:159], v[198:201], 0
	v_mfma_f32_16x16x32_bf16 v[12:15], v[138:141], v[206:209], 0
	v_mfma_f32_16x16x32_bf16 v[8:11], v[156:159], v[206:209], 0
	v_mfma_f32_16x16x32_bf16 v[60:63], v[142:145], v[184:187], v[60:63]
	v_mfma_f32_16x16x32_bf16 v[56:59], v[160:163], v[184:187], v[56:59]
	v_mfma_f32_16x16x32_bf16 v[44:47], v[142:145], v[194:197], v[44:47]
	v_mfma_f32_16x16x32_bf16 v[40:43], v[160:163], v[194:197], v[40:43]
	v_mfma_f32_16x16x32_bf16 v[28:31], v[142:145], v[202:205], v[28:31]
	v_mfma_f32_16x16x32_bf16 v[24:27], v[160:163], v[202:205], v[24:27]
	v_mfma_f32_16x16x32_bf16 v[12:15], v[142:145], v[210:213], v[12:15]
	v_mfma_f32_16x16x32_bf16 v[8:11], v[160:163], v[210:213], v[8:11]
	s_setprio 0
	s_setprio 1
	v_mfma_f32_16x16x32_bf16 v[52:55], v[164:167], v[180:183], 0
	v_mfma_f32_16x16x32_bf16 v[48:51], v[172:175], v[180:183], 0
	v_mfma_f32_16x16x32_bf16 v[36:39], v[164:167], v[190:193], 0
	v_mfma_f32_16x16x32_bf16 v[32:35], v[172:175], v[190:193], 0
	v_mfma_f32_16x16x32_bf16 v[20:23], v[164:167], v[198:201], 0
	v_mfma_f32_16x16x32_bf16 v[16:19], v[172:175], v[198:201], 0
	v_mfma_f32_16x16x32_bf16 v[4:7], v[164:167], v[206:209], 0
	v_mfma_f32_16x16x32_bf16 v[0:3], v[172:175], v[206:209], 0
	v_mfma_f32_16x16x32_bf16 v[52:55], v[168:171], v[184:187], v[52:55]
	v_mfma_f32_16x16x32_bf16 v[48:51], v[176:179], v[184:187], v[48:51]
	v_mfma_f32_16x16x32_bf16 v[36:39], v[168:171], v[194:197], v[36:39]
	v_mfma_f32_16x16x32_bf16 v[32:35], v[176:179], v[194:197], v[32:35]
	v_mfma_f32_16x16x32_bf16 v[20:23], v[168:171], v[202:205], v[20:23]
	v_mfma_f32_16x16x32_bf16 v[16:19], v[176:179], v[202:205], v[16:19]
	v_mfma_f32_16x16x32_bf16 v[4:7], v[168:171], v[210:213], v[4:7]
	v_mfma_f32_16x16x32_bf16 v[0:3], v[176:179], v[210:213], v[0:3]
	s_setprio 0
	s_barrier
	s_add_i32 s59, 0, 0x18000
	v_add_u32_e32 v155, s59, v147
	s_add_i32 s60, 0, 0x1c000
	ds_read_b128 v[138:141], v155
	ds_read_b128 v[142:145], v155 offset:1024
	ds_read_b128 v[156:159], v155 offset:2048
	ds_read_b128 v[160:163], v155 offset:3072
	v_add_u32_e32 v155, s60, v147
	ds_read_b128 v[164:167], v155
	ds_read_b128 v[168:171], v155 offset:1024
	ds_read_b128 v[172:175], v155 offset:2048
	ds_read_b128 v[176:179], v155 offset:3072
	s_add_u32 s34, s34, 0x20000
	s_addc_u32 s35, s35, 0
	s_mov_b32 m0, s39
	v_lshl_add_u64 v[222:223], s[34:35], 0, v[128:129]
	ds_read_b128 v[180:183], v154 offset:32768
	ds_read_b128 v[184:187], v154 offset:33792
	ds_read_b128 v[190:193], v154 offset:34816
	ds_read_b128 v[194:197], v154 offset:35840
	ds_read_b128 v[198:201], v154 offset:36864
	ds_read_b128 v[202:205], v154 offset:37888
	ds_read_b128 v[206:209], v154 offset:38912
	ds_read_b128 v[210:213], v154 offset:39936
	global_load_lds_dwordx4 v[222:223], off
	v_lshl_add_u64 v[222:223], s[34:35], 0, v[130:131]
	s_mov_b32 m0, s40
	s_nop 0
	global_load_lds_dwordx4 v[222:223], off
	s_waitcnt vmcnt(8)
	s_waitcnt lgkmcnt(0)
	s_barrier
	s_setprio 1
	s_waitcnt lgkmcnt(0)
	v_mfma_f32_16x16x32_bf16 v[120:123], v[138:141], v[180:183], v[120:123]
	v_mfma_f32_16x16x32_bf16 v[124:127], v[156:159], v[180:183], v[124:127]
	v_mfma_f32_16x16x32_bf16 v[108:111], v[138:141], v[190:193], v[108:111]
	v_mfma_f32_16x16x32_bf16 v[104:107], v[156:159], v[190:193], v[104:107]
	v_mfma_f32_16x16x32_bf16 v[92:95], v[138:141], v[198:201], v[92:95]
	v_mfma_f32_16x16x32_bf16 v[88:91], v[156:159], v[198:201], v[88:91]
	v_mfma_f32_16x16x32_bf16 v[76:79], v[138:141], v[206:209], v[76:79]
	v_mfma_f32_16x16x32_bf16 v[72:75], v[156:159], v[206:209], v[72:75]
	v_mfma_f32_16x16x32_bf16 v[120:123], v[142:145], v[184:187], v[120:123]
	v_mfma_f32_16x16x32_bf16 v[124:127], v[160:163], v[184:187], v[124:127]
	v_mfma_f32_16x16x32_bf16 v[108:111], v[142:145], v[194:197], v[108:111]
	v_mfma_f32_16x16x32_bf16 v[104:107], v[160:163], v[194:197], v[104:107]
	v_mfma_f32_16x16x32_bf16 v[92:95], v[142:145], v[202:205], v[92:95]
	v_mfma_f32_16x16x32_bf16 v[88:91], v[160:163], v[202:205], v[88:91]
	v_mfma_f32_16x16x32_bf16 v[76:79], v[142:145], v[210:213], v[76:79]
	v_mfma_f32_16x16x32_bf16 v[72:75], v[160:163], v[210:213], v[72:75]
	s_setprio 0
	s_setprio 1
	v_mfma_f32_16x16x32_bf16 v[116:119], v[164:167], v[180:183], v[116:119]
	v_mfma_f32_16x16x32_bf16 v[112:115], v[172:175], v[180:183], v[112:115]
	v_mfma_f32_16x16x32_bf16 v[100:103], v[164:167], v[190:193], v[100:103]
	v_mfma_f32_16x16x32_bf16 v[96:99], v[172:175], v[190:193], v[96:99]
	v_mfma_f32_16x16x32_bf16 v[84:87], v[164:167], v[198:201], v[84:87]
	v_mfma_f32_16x16x32_bf16 v[80:83], v[172:175], v[198:201], v[80:83]
	v_mfma_f32_16x16x32_bf16 v[68:71], v[164:167], v[206:209], v[68:71]
	v_mfma_f32_16x16x32_bf16 v[64:67], v[172:175], v[206:209], v[64:67]
	v_mfma_f32_16x16x32_bf16 v[116:119], v[168:171], v[184:187], v[116:119]
	v_mfma_f32_16x16x32_bf16 v[112:115], v[176:179], v[184:187], v[112:115]
	v_mfma_f32_16x16x32_bf16 v[100:103], v[168:171], v[194:197], v[100:103]
	v_mfma_f32_16x16x32_bf16 v[96:99], v[176:179], v[194:197], v[96:99]
	v_mfma_f32_16x16x32_bf16 v[84:87], v[168:171], v[202:205], v[84:87]
	v_mfma_f32_16x16x32_bf16 v[80:83], v[176:179], v[202:205], v[80:83]
	v_mfma_f32_16x16x32_bf16 v[68:71], v[168:171], v[210:213], v[68:71]
	v_mfma_f32_16x16x32_bf16 v[64:67], v[176:179], v[210:213], v[64:67]
	s_setprio 0
	s_barrier
	s_add_i32 s34, s59, s29
	v_lshl_add_u64 v[214:215], v[214:215], 0, s[12:13]
	s_mov_b32 m0, s34
	ds_read_b128 v[180:183], v154 offset:49152
	ds_read_b128 v[184:187], v154 offset:50176
	ds_read_b128 v[190:193], v154 offset:51200
	ds_read_b128 v[194:197], v154 offset:52224
	ds_read_b128 v[198:201], v154 offset:53248
	ds_read_b128 v[202:205], v154 offset:54272
	ds_read_b128 v[206:209], v154 offset:55296
	ds_read_b128 v[210:213], v154 offset:56320
	global_load_lds_dwordx4 v[214:215], off
	s_add_i32 m0, s34, 0x2000
	s_add_u32 s4, s4, 0x20080
	v_lshl_add_u64 v[214:215], v[216:217], 0, s[12:13]
	s_addc_u32 s5, s5, 0
	s_add_i32 s34, s60, s29
	global_load_lds_dwordx4 v[214:215], off
	v_lshl_add_u64 v[214:215], s[4:5], 0, v[128:129]
	s_mov_b32 m0, s34
	s_nop 0
	global_load_lds_dwordx4 v[214:215], off
	v_lshl_add_u64 v[214:215], s[4:5], 0, v[130:131]
	s_add_i32 m0, s34, 0x2000
	s_nop 0
	global_load_lds_dwordx4 v[214:215], off
	v_lshl_add_u64 v[214:215], v[218:219], 0, s[12:13]
	s_mov_b32 m0, s46
	s_nop 0
	global_load_lds_dwordx4 v[214:215], off
	v_lshl_add_u64 v[214:215], v[220:221], 0, s[12:13]
	s_mov_b32 m0, s47
	s_nop 0
	global_load_lds_dwordx4 v[214:215], off
	s_waitcnt vmcnt(8)
	s_waitcnt lgkmcnt(0)
	s_barrier
	s_setprio 1
	s_waitcnt lgkmcnt(0)
	v_mfma_f32_16x16x32_bf16 v[60:63], v[138:141], v[180:183], v[60:63]
	v_mfma_f32_16x16x32_bf16 v[56:59], v[156:159], v[180:183], v[56:59]
	v_mfma_f32_16x16x32_bf16 v[44:47], v[138:141], v[190:193], v[44:47]
	v_mfma_f32_16x16x32_bf16 v[40:43], v[156:159], v[190:193], v[40:43]
	v_mfma_f32_16x16x32_bf16 v[28:31], v[138:141], v[198:201], v[28:31]
	v_mfma_f32_16x16x32_bf16 v[24:27], v[156:159], v[198:201], v[24:27]
	v_mfma_f32_16x16x32_bf16 v[12:15], v[138:141], v[206:209], v[12:15]
	v_mfma_f32_16x16x32_bf16 v[8:11], v[156:159], v[206:209], v[8:11]
	v_mfma_f32_16x16x32_bf16 v[60:63], v[142:145], v[184:187], v[60:63]
	v_mfma_f32_16x16x32_bf16 v[56:59], v[160:163], v[184:187], v[56:59]
	v_mfma_f32_16x16x32_bf16 v[44:47], v[142:145], v[194:197], v[44:47]
	v_mfma_f32_16x16x32_bf16 v[40:43], v[160:163], v[194:197], v[40:43]
	v_mfma_f32_16x16x32_bf16 v[28:31], v[142:145], v[202:205], v[28:31]
	v_mfma_f32_16x16x32_bf16 v[24:27], v[160:163], v[202:205], v[24:27]
	v_mfma_f32_16x16x32_bf16 v[12:15], v[142:145], v[210:213], v[12:15]
	v_mfma_f32_16x16x32_bf16 v[8:11], v[160:163], v[210:213], v[8:11]
	s_setprio 0
	s_setprio 1
	v_mfma_f32_16x16x32_bf16 v[52:55], v[164:167], v[180:183], v[52:55]
	v_mfma_f32_16x16x32_bf16 v[48:51], v[172:175], v[180:183], v[48:51]
	v_mfma_f32_16x16x32_bf16 v[36:39], v[164:167], v[190:193], v[36:39]
	v_mfma_f32_16x16x32_bf16 v[32:35], v[172:175], v[190:193], v[32:35]
	v_mfma_f32_16x16x32_bf16 v[20:23], v[164:167], v[198:201], v[20:23]
	v_mfma_f32_16x16x32_bf16 v[16:19], v[172:175], v[198:201], v[16:19]
	v_mfma_f32_16x16x32_bf16 v[4:7], v[164:167], v[206:209], v[4:7]
	v_mfma_f32_16x16x32_bf16 v[0:3], v[172:175], v[206:209], v[0:3]
	v_mfma_f32_16x16x32_bf16 v[52:55], v[168:171], v[184:187], v[52:55]
	v_mfma_f32_16x16x32_bf16 v[48:51], v[176:179], v[184:187], v[48:51]
	v_mfma_f32_16x16x32_bf16 v[36:39], v[168:171], v[194:197], v[36:39]
	v_mfma_f32_16x16x32_bf16 v[32:35], v[176:179], v[194:197], v[32:35]
	v_mfma_f32_16x16x32_bf16 v[20:23], v[168:171], v[202:205], v[20:23]
	v_mfma_f32_16x16x32_bf16 v[16:19], v[176:179], v[202:205], v[16:19]
	v_mfma_f32_16x16x32_bf16 v[4:7], v[168:171], v[210:213], v[4:7]
	v_mfma_f32_16x16x32_bf16 v[0:3], v[176:179], v[210:213], v[0:3]
	s_setprio 0
	s_barrier
	s_add_u32 s30, s30, 0x100
	s_addc_u32 s31, s31, 0
	s_add_u32 s21, s21, 0x100
	s_addc_u32 s23, s23, 0
	s_cmp_ge_i32 s58, s41
	s_mov_b32 s4, s58
	s_cbranch_scc0 .LBB0_1266
	s_branch .LBB0_1267

.LBB0_1368:
	s_andn2_b64 vcc, exec, s[18:19]
	s_waitcnt lgkmcnt(0)
	s_waitcnt vmcnt(0)
	s_cbranch_vccnz .Lpz_zero_3
	s_add_u32 s34, s4, 0x40080
	s_addc_u32 s35, s5, 0
	s_add_u32 s23, s36, 0x100
	s_addc_u32 s25, s37, 0
	s_mov_b32 s4, 0
	ds_read_b128 v[138:141], v145
	ds_read_b128 v[150:153], v145 offset:1024
	ds_read_b128 v[154:157], v145 offset:2048
	ds_read_b128 v[158:161], v145 offset:3072
	ds_read_b128 v[162:165], v146
	ds_read_b128 v[166:169], v146 offset:1024
	ds_read_b128 v[170:173], v146 offset:2048
	ds_read_b128 v[174:177], v146 offset:3072
	s_add_i32 s31, s4, 2
	s_add_u32 s5, s34, 0xfffc0080
	s_addc_u32 s36, s35, -1
	s_cmp_eq_u32 s50, s4
	s_cselect_b32 s4, s28, s23
	s_cselect_b32 s37, s27, s36
	s_cselect_b32 s36, s26, s5
	s_cselect_b32 s5, s29, s25
	v_lshl_add_u64 v[186:187], s[34:35], 0, v[132:133]
	s_add_i32 m0, s42, 0xc000
	ds_read_b128 v[178:181], v147
	ds_read_b128 v[182:185], v147 offset:1024
	ds_read_b128 v[190:193], v147 offset:2048
	ds_read_b128 v[194:197], v147 offset:3072
	ds_read_b128 v[198:201], v147 offset:4096
	ds_read_b128 v[202:205], v147 offset:5120
	ds_read_b128 v[206:209], v147 offset:6144
	ds_read_b128 v[210:213], v147 offset:7168
	global_load_lds_dwordx4 v[186:187], off
	v_lshl_add_u64 v[186:187], s[34:35], 0, v[134:135]
	s_add_i32 m0, s42, 0xe000
	s_nop 0
	global_load_lds_dwordx4 v[186:187], off
	s_waitcnt vmcnt(8)
	s_waitcnt lgkmcnt(0)
	s_barrier
	s_setprio 1
	s_waitcnt lgkmcnt(0)
	v_mfma_f32_16x16x32_bf16 v[120:123], v[138:141], v[178:181], 0
	v_mfma_f32_16x16x32_bf16 v[124:127], v[154:157], v[178:181], 0
	v_mfma_f32_16x16x32_bf16 v[108:111], v[138:141], v[190:193], 0
	v_mfma_f32_16x16x32_bf16 v[104:107], v[154:157], v[190:193], 0
	v_mfma_f32_16x16x32_bf16 v[92:95], v[138:141], v[198:201], 0
	v_mfma_f32_16x16x32_bf16 v[88:91], v[154:157], v[198:201], 0
	v_mfma_f32_16x16x32_bf16 v[76:79], v[138:141], v[206:209], 0
	v_mfma_f32_16x16x32_bf16 v[72:75], v[154:157], v[206:209], 0
	v_mfma_f32_16x16x32_bf16 v[120:123], v[150:153], v[182:185], v[120:123]
	v_mfma_f32_16x16x32_bf16 v[124:127], v[158:161], v[182:185], v[124:127]
	v_mfma_f32_16x16x32_bf16 v[108:111], v[150:153], v[194:197], v[108:111]
	v_mfma_f32_16x16x32_bf16 v[104:107], v[158:161], v[194:197], v[104:107]
	v_mfma_f32_16x16x32_bf16 v[92:95], v[150:153], v[202:205], v[92:95]
	v_mfma_f32_16x16x32_bf16 v[88:91], v[158:161], v[202:205], v[88:91]
	v_mfma_f32_16x16x32_bf16 v[76:79], v[150:153], v[210:213], v[76:79]
	v_mfma_f32_16x16x32_bf16 v[72:75], v[158:161], v[210:213], v[72:75]
	s_setprio 0
	s_setprio 1
	v_mfma_f32_16x16x32_bf16 v[116:119], v[162:165], v[178:181], 0
	v_mfma_f32_16x16x32_bf16 v[112:115], v[170:173], v[178:181], 0
	v_mfma_f32_16x16x32_bf16 v[100:103], v[162:165], v[190:193], 0
	v_mfma_f32_16x16x32_bf16 v[96:99], v[170:173], v[190:193], 0
	v_mfma_f32_16x16x32_bf16 v[84:87], v[162:165], v[198:201], 0
	v_mfma_f32_16x16x32_bf16 v[80:83], v[170:173], v[198:201], 0
	v_mfma_f32_16x16x32_bf16 v[68:71], v[162:165], v[206:209], 0
	v_mfma_f32_16x16x32_bf16 v[64:67], v[170:173], v[206:209], 0
	v_mfma_f32_16x16x32_bf16 v[116:119], v[166:169], v[182:185], v[116:119]
	v_mfma_f32_16x16x32_bf16 v[112:115], v[174:177], v[182:185], v[112:115]
	v_mfma_f32_16x16x32_bf16 v[100:103], v[166:169], v[194:197], v[100:103]
	v_mfma_f32_16x16x32_bf16 v[96:99], v[174:177], v[194:197], v[96:99]
	v_mfma_f32_16x16x32_bf16 v[84:87], v[166:169], v[202:205], v[84:87]
	v_mfma_f32_16x16x32_bf16 v[80:83], v[174:177], v[202:205], v[80:83]
	v_mfma_f32_16x16x32_bf16 v[68:71], v[166:169], v[210:213], v[68:71]
	v_mfma_f32_16x16x32_bf16 v[64:67], v[174:177], v[210:213], v[64:67]
	s_setprio 0
	s_barrier
	s_add_i32 s59, s55, s41
	v_lshl_add_u64 v[186:187], s[4:5], 0, v[128:129]
	s_mov_b32 m0, s59
	ds_read_b128 v[178:181], v147 offset:16384
	ds_read_b128 v[182:185], v147 offset:17408
	ds_read_b128 v[190:193], v147 offset:18432
	ds_read_b128 v[194:197], v147 offset:19456
	ds_read_b128 v[198:201], v147 offset:20480
	ds_read_b128 v[202:205], v147 offset:21504
	ds_read_b128 v[206:209], v147 offset:22528
	ds_read_b128 v[210:213], v147 offset:23552
	global_load_lds_dwordx4 v[186:187], off
	s_add_i32 m0, s59, 0x2000
	s_add_u32 s60, s4, 0x40000
	v_lshl_add_u64 v[214:215], s[4:5], 0, v[130:131]
	s_addc_u32 s61, s5, 0
	s_add_i32 s59, s56, s41
	global_load_lds_dwordx4 v[214:215], off
	v_lshl_add_u64 v[216:217], s[60:61], 0, v[128:129]
	s_mov_b32 m0, s59
	v_lshl_add_u64 v[218:219], s[36:37], 0, v[130:131]
	global_load_lds_dwordx4 v[216:217], off
	v_lshl_add_u64 v[216:217], s[60:61], 0, v[130:131]
	s_add_i32 m0, s59, 0x2000
	s_nop 0
	global_load_lds_dwordx4 v[216:217], off
	v_lshl_add_u64 v[216:217], s[36:37], 0, v[128:129]
	s_mov_b32 m0, s42
	s_nop 0
	global_load_lds_dwordx4 v[216:217], off
	s_mov_b32 m0, s43
	s_nop 0
	global_load_lds_dwordx4 v[218:219], off
	s_waitcnt vmcnt(8)
	s_waitcnt lgkmcnt(0)
	s_barrier
	s_setprio 1
	s_waitcnt lgkmcnt(0)
	v_mfma_f32_16x16x32_bf16 v[60:63], v[138:141], v[178:181], 0
	v_mfma_f32_16x16x32_bf16 v[56:59], v[154:157], v[178:181], 0
	v_mfma_f32_16x16x32_bf16 v[44:47], v[138:141], v[190:193], 0
	v_mfma_f32_16x16x32_bf16 v[40:43], v[154:157], v[190:193], 0
	v_mfma_f32_16x16x32_bf16 v[28:31], v[138:141], v[198:201], 0
	v_mfma_f32_16x16x32_bf16 v[24:27], v[154:157], v[198:201], 0
	v_mfma_f32_16x16x32_bf16 v[12:15], v[138:141], v[206:209], 0
	v_mfma_f32_16x16x32_bf16 v[8:11], v[154:157], v[206:209], 0
	v_mfma_f32_16x16x32_bf16 v[60:63], v[150:153], v[182:185], v[60:63]
	v_mfma_f32_16x16x32_bf16 v[56:59], v[158:161], v[182:185], v[56:59]
	v_mfma_f32_16x16x32_bf16 v[44:47], v[150:153], v[194:197], v[44:47]
	v_mfma_f32_16x16x32_bf16 v[40:43], v[158:161], v[194:197], v[40:43]
	v_mfma_f32_16x16x32_bf16 v[28:31], v[150:153], v[202:205], v[28:31]
	v_mfma_f32_16x16x32_bf16 v[24:27], v[158:161], v[202:205], v[24:27]
	v_mfma_f32_16x16x32_bf16 v[12:15], v[150:153], v[210:213], v[12:15]
	v_mfma_f32_16x16x32_bf16 v[8:11], v[158:161], v[210:213], v[8:11]
	s_setprio 0
	s_setprio 1
	v_mfma_f32_16x16x32_bf16 v[52:55], v[162:165], v[178:181], 0
	v_mfma_f32_16x16x32_bf16 v[48:51], v[170:173], v[178:181], 0
	v_mfma_f32_16x16x32_bf16 v[36:39], v[162:165], v[190:193], 0
	v_mfma_f32_16x16x32_bf16 v[32:35], v[170:173], v[190:193], 0
	v_mfma_f32_16x16x32_bf16 v[20:23], v[162:165], v[198:201], 0
	v_mfma_f32_16x16x32_bf16 v[16:19], v[170:173], v[198:201], 0
	v_mfma_f32_16x16x32_bf16 v[4:7], v[162:165], v[206:209], 0
	v_mfma_f32_16x16x32_bf16 v[0:3], v[170:173], v[206:209], 0
	v_mfma_f32_16x16x32_bf16 v[52:55], v[166:169], v[182:185], v[52:55]
	v_mfma_f32_16x16x32_bf16 v[48:51], v[174:177], v[182:185], v[48:51]
	v_mfma_f32_16x16x32_bf16 v[36:39], v[166:169], v[194:197], v[36:39]
	v_mfma_f32_16x16x32_bf16 v[32:35], v[174:177], v[194:197], v[32:35]
	v_mfma_f32_16x16x32_bf16 v[20:23], v[166:169], v[202:205], v[20:23]
	v_mfma_f32_16x16x32_bf16 v[16:19], v[174:177], v[202:205], v[16:19]
	v_mfma_f32_16x16x32_bf16 v[4:7], v[166:169], v[210:213], v[4:7]
	v_mfma_f32_16x16x32_bf16 v[0:3], v[174:177], v[210:213], v[0:3]
	s_setprio 0
	s_barrier
	s_add_i32 s59, 0, 0x18000
	v_add_u32_e32 v149, s59, v143
	s_add_i32 s60, 0, 0x1c000
	ds_read_b128 v[138:141], v149
	ds_read_b128 v[150:153], v149 offset:1024
	ds_read_b128 v[154:157], v149 offset:2048
	ds_read_b128 v[158:161], v149 offset:3072
	v_add_u32_e32 v149, s60, v143
	ds_read_b128 v[162:165], v149
	ds_read_b128 v[166:169], v149 offset:1024
	ds_read_b128 v[170:173], v149 offset:2048
	ds_read_b128 v[174:177], v149 offset:3072
	s_add_u32 s36, s36, 0x40000
	s_addc_u32 s37, s37, 0
	s_mov_b32 m0, s44
	v_lshl_add_u64 v[220:221], s[36:37], 0, v[128:129]
	ds_read_b128 v[178:181], v147 offset:32768
	ds_read_b128 v[182:185], v147 offset:33792
	ds_read_b128 v[190:193], v147 offset:34816
	ds_read_b128 v[194:197], v147 offset:35840
	ds_read_b128 v[198:201], v147 offset:36864
	ds_read_b128 v[202:205], v147 offset:37888
	ds_read_b128 v[206:209], v147 offset:38912
	ds_read_b128 v[210:213], v147 offset:39936
	global_load_lds_dwordx4 v[220:221], off
	v_lshl_add_u64 v[220:221], s[36:37], 0, v[130:131]
	s_mov_b32 m0, s45
	s_nop 0
	global_load_lds_dwordx4 v[220:221], off
	s_waitcnt vmcnt(8)
	s_waitcnt lgkmcnt(0)
	s_barrier
	s_setprio 1
	s_waitcnt lgkmcnt(0)
	v_mfma_f32_16x16x32_bf16 v[120:123], v[138:141], v[178:181], v[120:123]
	v_mfma_f32_16x16x32_bf16 v[124:127], v[154:157], v[178:181], v[124:127]
	v_mfma_f32_16x16x32_bf16 v[108:111], v[138:141], v[190:193], v[108:111]
	v_mfma_f32_16x16x32_bf16 v[104:107], v[154:157], v[190:193], v[104:107]
	v_mfma_f32_16x16x32_bf16 v[92:95], v[138:141], v[198:201], v[92:95]
	v_mfma_f32_16x16x32_bf16 v[88:91], v[154:157], v[198:201], v[88:91]
	v_mfma_f32_16x16x32_bf16 v[76:79], v[138:141], v[206:209], v[76:79]
	v_mfma_f32_16x16x32_bf16 v[72:75], v[154:157], v[206:209], v[72:75]
	v_mfma_f32_16x16x32_bf16 v[120:123], v[150:153], v[182:185], v[120:123]
	v_mfma_f32_16x16x32_bf16 v[124:127], v[158:161], v[182:185], v[124:127]
	v_mfma_f32_16x16x32_bf16 v[108:111], v[150:153], v[194:197], v[108:111]
	v_mfma_f32_16x16x32_bf16 v[104:107], v[158:161], v[194:197], v[104:107]
	v_mfma_f32_16x16x32_bf16 v[92:95], v[150:153], v[202:205], v[92:95]
	v_mfma_f32_16x16x32_bf16 v[88:91], v[158:161], v[202:205], v[88:91]
	v_mfma_f32_16x16x32_bf16 v[76:79], v[150:153], v[210:213], v[76:79]
	v_mfma_f32_16x16x32_bf16 v[72:75], v[158:161], v[210:213], v[72:75]
	s_setprio 0
	s_setprio 1
	v_mfma_f32_16x16x32_bf16 v[116:119], v[162:165], v[178:181], v[116:119]
	v_mfma_f32_16x16x32_bf16 v[112:115], v[170:173], v[178:181], v[112:115]
	v_mfma_f32_16x16x32_bf16 v[100:103], v[162:165], v[190:193], v[100:103]
	v_mfma_f32_16x16x32_bf16 v[96:99], v[170:173], v[190:193], v[96:99]
	v_mfma_f32_16x16x32_bf16 v[84:87], v[162:165], v[198:201], v[84:87]
	v_mfma_f32_16x16x32_bf16 v[80:83], v[170:173], v[198:201], v[80:83]
	v_mfma_f32_16x16x32_bf16 v[68:71], v[162:165], v[206:209], v[68:71]
	v_mfma_f32_16x16x32_bf16 v[64:67], v[170:173], v[206:209], v[64:67]
	v_mfma_f32_16x16x32_bf16 v[116:119], v[166:169], v[182:185], v[116:119]
	v_mfma_f32_16x16x32_bf16 v[112:115], v[174:177], v[182:185], v[112:115]
	v_mfma_f32_16x16x32_bf16 v[100:103], v[166:169], v[194:197], v[100:103]
	v_mfma_f32_16x16x32_bf16 v[96:99], v[174:177], v[194:197], v[96:99]
	v_mfma_f32_16x16x32_bf16 v[84:87], v[166:169], v[202:205], v[84:87]
	v_mfma_f32_16x16x32_bf16 v[80:83], v[174:177], v[202:205], v[80:83]
	v_mfma_f32_16x16x32_bf16 v[68:71], v[166:169], v[210:213], v[68:71]
	v_mfma_f32_16x16x32_bf16 v[64:67], v[174:177], v[210:213], v[64:67]
	s_setprio 0
	s_barrier
	s_add_i32 s36, s59, s41
	v_lshl_add_u64 v[186:187], v[186:187], 0, s[16:17]
	s_mov_b32 m0, s36
	ds_read_b128 v[178:181], v147 offset:49152
	ds_read_b128 v[182:185], v147 offset:50176
	ds_read_b128 v[190:193], v147 offset:51200
	ds_read_b128 v[194:197], v147 offset:52224
	ds_read_b128 v[198:201], v147 offset:53248
	ds_read_b128 v[202:205], v147 offset:54272
	ds_read_b128 v[206:209], v147 offset:55296
	ds_read_b128 v[210:213], v147 offset:56320
	global_load_lds_dwordx4 v[186:187], off
	s_add_i32 m0, s36, 0x2000
	s_add_u32 s4, s4, 0x40080
	v_lshl_add_u64 v[186:187], v[214:215], 0, s[16:17]
	s_addc_u32 s5, s5, 0
	s_add_i32 s36, s60, s41
	global_load_lds_dwordx4 v[186:187], off
	v_lshl_add_u64 v[186:187], s[4:5], 0, v[128:129]
	s_mov_b32 m0, s36
	s_nop 0
	global_load_lds_dwordx4 v[186:187], off
	v_lshl_add_u64 v[186:187], s[4:5], 0, v[130:131]
	s_add_i32 m0, s36, 0x2000
	s_nop 0
	global_load_lds_dwordx4 v[186:187], off
	v_lshl_add_u64 v[186:187], v[216:217], 0, s[16:17]
	s_mov_b32 m0, s48
	s_nop 0
	global_load_lds_dwordx4 v[186:187], off
	v_lshl_add_u64 v[186:187], v[218:219], 0, s[16:17]
	s_mov_b32 m0, s49
	s_nop 0
	global_load_lds_dwordx4 v[186:187], off
	s_waitcnt vmcnt(8)
	s_waitcnt lgkmcnt(0)
	s_barrier
	s_setprio 1
	s_waitcnt lgkmcnt(0)
	v_mfma_f32_16x16x32_bf16 v[60:63], v[138:141], v[178:181], v[60:63]
	v_mfma_f32_16x16x32_bf16 v[56:59], v[154:157], v[178:181], v[56:59]
	v_mfma_f32_16x16x32_bf16 v[44:47], v[138:141], v[190:193], v[44:47]
	v_mfma_f32_16x16x32_bf16 v[40:43], v[154:157], v[190:193], v[40:43]
	v_mfma_f32_16x16x32_bf16 v[28:31], v[138:141], v[198:201], v[28:31]
	v_mfma_f32_16x16x32_bf16 v[24:27], v[154:157], v[198:201], v[24:27]
	v_mfma_f32_16x16x32_bf16 v[12:15], v[138:141], v[206:209], v[12:15]
	v_mfma_f32_16x16x32_bf16 v[8:11], v[154:157], v[206:209], v[8:11]
	v_mfma_f32_16x16x32_bf16 v[60:63], v[150:153], v[182:185], v[60:63]
	v_mfma_f32_16x16x32_bf16 v[56:59], v[158:161], v[182:185], v[56:59]
	v_mfma_f32_16x16x32_bf16 v[44:47], v[150:153], v[194:197], v[44:47]
	v_mfma_f32_16x16x32_bf16 v[40:43], v[158:161], v[194:197], v[40:43]
	v_mfma_f32_16x16x32_bf16 v[28:31], v[150:153], v[202:205], v[28:31]
	v_mfma_f32_16x16x32_bf16 v[24:27], v[158:161], v[202:205], v[24:27]
	v_mfma_f32_16x16x32_bf16 v[12:15], v[150:153], v[210:213], v[12:15]
	v_mfma_f32_16x16x32_bf16 v[8:11], v[158:161], v[210:213], v[8:11]
	s_setprio 0
	s_setprio 1
	v_mfma_f32_16x16x32_bf16 v[52:55], v[162:165], v[178:181], v[52:55]
	v_mfma_f32_16x16x32_bf16 v[48:51], v[170:173], v[178:181], v[48:51]
	v_mfma_f32_16x16x32_bf16 v[36:39], v[162:165], v[190:193], v[36:39]
	v_mfma_f32_16x16x32_bf16 v[32:35], v[170:173], v[190:193], v[32:35]
	v_mfma_f32_16x16x32_bf16 v[20:23], v[162:165], v[198:201], v[20:23]
	v_mfma_f32_16x16x32_bf16 v[16:19], v[170:173], v[198:201], v[16:19]
	v_mfma_f32_16x16x32_bf16 v[4:7], v[162:165], v[206:209], v[4:7]
	v_mfma_f32_16x16x32_bf16 v[0:3], v[170:173], v[206:209], v[0:3]
	v_mfma_f32_16x16x32_bf16 v[52:55], v[166:169], v[182:185], v[52:55]
	v_mfma_f32_16x16x32_bf16 v[48:51], v[174:177], v[182:185], v[48:51]
	v_mfma_f32_16x16x32_bf16 v[36:39], v[166:169], v[194:197], v[36:39]
	v_mfma_f32_16x16x32_bf16 v[32:35], v[174:177], v[194:197], v[32:35]
	v_mfma_f32_16x16x32_bf16 v[20:23], v[166:169], v[202:205], v[20:23]
	v_mfma_f32_16x16x32_bf16 v[16:19], v[174:177], v[202:205], v[16:19]
	v_mfma_f32_16x16x32_bf16 v[4:7], v[166:169], v[210:213], v[4:7]
	v_mfma_f32_16x16x32_bf16 v[0:3], v[174:177], v[210:213], v[0:3]
	s_setprio 0
	s_barrier
	s_add_u32 s34, s34, 0x100
	s_addc_u32 s35, s35, 0
	s_add_u32 s23, s23, 0x100
	s_addc_u32 s25, s25, 0
	s_cmp_ge_i32 s31, s47
	s_mov_b32 s4, s31
	s_cbranch_scc0 .LBB0_1370
	s_branch .LBB0_1371

.LBB0_1462:
	s_andn2_b64 vcc, exec, s[14:15]
	s_waitcnt vmcnt(0)
	s_cbranch_vccnz .Lpz_zero_4
	s_add_u32 s30, s4, 0x40080
	s_addc_u32 s31, s5, 0
	s_add_u32 s19, s34, 0x100
	s_addc_u32 s21, s35, 0
	s_mov_b32 s4, 0
	ds_read_b128 v[148:151], v143
	ds_read_b128 v[152:155], v143 offset:1024
	ds_read_b128 v[156:159], v143 offset:2048
	ds_read_b128 v[160:163], v143 offset:3072
	ds_read_b128 v[164:167], v144
	ds_read_b128 v[168:171], v144 offset:1024
	ds_read_b128 v[172:175], v144 offset:2048
	ds_read_b128 v[176:179], v144 offset:3072
	s_add_i32 s57, s4, 2
	s_add_u32 s5, s30, 0xfffc0080
	s_addc_u32 s34, s31, -1
	s_cmp_eq_u32 s46, s4
	s_cselect_b32 s4, s24, s19
	s_cselect_b32 s35, s23, s34
	s_cselect_b32 s34, s22, s5
	s_cselect_b32 s5, s25, s21
	v_lshl_add_u64 v[138:139], s[30:31], 0, v[132:133]
	s_add_i32 m0, s27, 0xc000
	ds_read_b128 v[180:183], v145
	ds_read_b128 v[184:187], v145 offset:1024
	ds_read_b128 v[190:193], v145 offset:2048
	ds_read_b128 v[194:197], v145 offset:3072
	ds_read_b128 v[198:201], v145 offset:4096
	ds_read_b128 v[202:205], v145 offset:5120
	ds_read_b128 v[206:209], v145 offset:6144
	ds_read_b128 v[210:213], v145 offset:7168
	global_load_lds_dwordx4 v[138:139], off
	v_lshl_add_u64 v[138:139], s[30:31], 0, v[134:135]
	s_add_i32 m0, s27, 0xe000
	s_nop 0
	global_load_lds_dwordx4 v[138:139], off
	s_waitcnt vmcnt(8)
	s_waitcnt lgkmcnt(0)
	s_barrier
	s_setprio 1
	s_waitcnt lgkmcnt(0)
	v_mfma_f32_16x16x32_bf16 v[116:119], v[148:151], v[180:183], 0
	v_mfma_f32_16x16x32_bf16 v[112:115], v[156:159], v[180:183], 0
	v_mfma_f32_16x16x32_bf16 v[100:103], v[148:151], v[190:193], 0
	v_mfma_f32_16x16x32_bf16 v[96:99], v[156:159], v[190:193], 0
	v_mfma_f32_16x16x32_bf16 v[84:87], v[148:151], v[198:201], 0
	v_mfma_f32_16x16x32_bf16 v[80:83], v[156:159], v[198:201], 0
	v_mfma_f32_16x16x32_bf16 v[68:71], v[148:151], v[206:209], 0
	v_mfma_f32_16x16x32_bf16 v[64:67], v[156:159], v[206:209], 0
	v_mfma_f32_16x16x32_bf16 v[116:119], v[152:155], v[184:187], v[116:119]
	v_mfma_f32_16x16x32_bf16 v[112:115], v[160:163], v[184:187], v[112:115]
	v_mfma_f32_16x16x32_bf16 v[100:103], v[152:155], v[194:197], v[100:103]
	v_mfma_f32_16x16x32_bf16 v[96:99], v[160:163], v[194:197], v[96:99]
	v_mfma_f32_16x16x32_bf16 v[84:87], v[152:155], v[202:205], v[84:87]
	v_mfma_f32_16x16x32_bf16 v[80:83], v[160:163], v[202:205], v[80:83]
	v_mfma_f32_16x16x32_bf16 v[68:71], v[152:155], v[210:213], v[68:71]
	v_mfma_f32_16x16x32_bf16 v[64:67], v[160:163], v[210:213], v[64:67]
	s_setprio 0
	s_setprio 1
	v_mfma_f32_16x16x32_bf16 v[124:127], v[164:167], v[180:183], 0
	v_mfma_f32_16x16x32_bf16 v[120:123], v[172:175], v[180:183], 0
	v_mfma_f32_16x16x32_bf16 v[108:111], v[164:167], v[190:193], 0
	v_mfma_f32_16x16x32_bf16 v[104:107], v[172:175], v[190:193], 0
	v_mfma_f32_16x16x32_bf16 v[92:95], v[164:167], v[198:201], 0
	v_mfma_f32_16x16x32_bf16 v[88:91], v[172:175], v[198:201], 0
	v_mfma_f32_16x16x32_bf16 v[76:79], v[164:167], v[206:209], 0
	v_mfma_f32_16x16x32_bf16 v[72:75], v[172:175], v[206:209], 0
	v_mfma_f32_16x16x32_bf16 v[124:127], v[168:171], v[184:187], v[124:127]
	v_mfma_f32_16x16x32_bf16 v[120:123], v[176:179], v[184:187], v[120:123]
	v_mfma_f32_16x16x32_bf16 v[108:111], v[168:171], v[194:197], v[108:111]
	v_mfma_f32_16x16x32_bf16 v[104:107], v[176:179], v[194:197], v[104:107]
	v_mfma_f32_16x16x32_bf16 v[92:95], v[168:171], v[202:205], v[92:95]
	v_mfma_f32_16x16x32_bf16 v[88:91], v[176:179], v[202:205], v[88:91]
	v_mfma_f32_16x16x32_bf16 v[76:79], v[168:171], v[210:213], v[76:79]
	v_mfma_f32_16x16x32_bf16 v[72:75], v[176:179], v[210:213], v[72:75]
	s_setprio 0
	s_barrier
	s_add_i32 s58, s52, s33
	v_lshl_add_u64 v[138:139], s[4:5], 0, v[128:129]
	s_mov_b32 m0, s58
	ds_read_b128 v[180:183], v145 offset:16384
	ds_read_b128 v[184:187], v145 offset:17408
	ds_read_b128 v[190:193], v145 offset:18432
	ds_read_b128 v[194:197], v145 offset:19456
	ds_read_b128 v[198:201], v145 offset:20480
	ds_read_b128 v[202:205], v145 offset:21504
	ds_read_b128 v[206:209], v145 offset:22528
	ds_read_b128 v[210:213], v145 offset:23552
	global_load_lds_dwordx4 v[138:139], off
	s_add_i32 m0, s58, 0x2000
	s_add_u32 s58, s4, 0x40000
	v_lshl_add_u64 v[214:215], s[4:5], 0, v[130:131]
	s_addc_u32 s59, s5, 0
	s_add_i32 s60, s53, s33
	global_load_lds_dwordx4 v[214:215], off
	v_lshl_add_u64 v[216:217], s[58:59], 0, v[128:129]
	s_mov_b32 m0, s60
	v_lshl_add_u64 v[218:219], s[34:35], 0, v[130:131]
	global_load_lds_dwordx4 v[216:217], off
	v_lshl_add_u64 v[216:217], s[58:59], 0, v[130:131]
	s_add_i32 m0, s60, 0x2000
	s_nop 0
	global_load_lds_dwordx4 v[216:217], off
	v_lshl_add_u64 v[216:217], s[34:35], 0, v[128:129]
	s_mov_b32 m0, s27
	s_nop 0
	global_load_lds_dwordx4 v[216:217], off
	s_mov_b32 m0, s29
	s_nop 0
	global_load_lds_dwordx4 v[218:219], off
	s_waitcnt vmcnt(8)
	s_waitcnt lgkmcnt(0)
	s_barrier
	s_setprio 1
	s_waitcnt lgkmcnt(0)
	v_mfma_f32_16x16x32_bf16 v[52:55], v[148:151], v[180:183], 0
	v_mfma_f32_16x16x32_bf16 v[48:51], v[156:159], v[180:183], 0
	v_mfma_f32_16x16x32_bf16 v[36:39], v[148:151], v[190:193], 0
	v_mfma_f32_16x16x32_bf16 v[32:35], v[156:159], v[190:193], 0
	v_mfma_f32_16x16x32_bf16 v[20:23], v[148:151], v[198:201], 0
	v_mfma_f32_16x16x32_bf16 v[16:19], v[156:159], v[198:201], 0
	v_mfma_f32_16x16x32_bf16 v[4:7], v[148:151], v[206:209], 0
	v_mfma_f32_16x16x32_bf16 v[0:3], v[156:159], v[206:209], 0
	v_mfma_f32_16x16x32_bf16 v[52:55], v[152:155], v[184:187], v[52:55]
	v_mfma_f32_16x16x32_bf16 v[48:51], v[160:163], v[184:187], v[48:51]
	v_mfma_f32_16x16x32_bf16 v[36:39], v[152:155], v[194:197], v[36:39]
	v_mfma_f32_16x16x32_bf16 v[32:35], v[160:163], v[194:197], v[32:35]
	v_mfma_f32_16x16x32_bf16 v[20:23], v[152:155], v[202:205], v[20:23]
	v_mfma_f32_16x16x32_bf16 v[16:19], v[160:163], v[202:205], v[16:19]
	v_mfma_f32_16x16x32_bf16 v[4:7], v[152:155], v[210:213], v[4:7]
	v_mfma_f32_16x16x32_bf16 v[0:3], v[160:163], v[210:213], v[0:3]
	s_setprio 0
	s_setprio 1
	v_mfma_f32_16x16x32_bf16 v[60:63], v[164:167], v[180:183], 0
	v_mfma_f32_16x16x32_bf16 v[56:59], v[172:175], v[180:183], 0
	v_mfma_f32_16x16x32_bf16 v[44:47], v[164:167], v[190:193], 0
	v_mfma_f32_16x16x32_bf16 v[40:43], v[172:175], v[190:193], 0
	v_mfma_f32_16x16x32_bf16 v[28:31], v[164:167], v[198:201], 0
	v_mfma_f32_16x16x32_bf16 v[24:27], v[172:175], v[198:201], 0
	v_mfma_f32_16x16x32_bf16 v[12:15], v[164:167], v[206:209], 0
	v_mfma_f32_16x16x32_bf16 v[8:11], v[172:175], v[206:209], 0
	v_mfma_f32_16x16x32_bf16 v[60:63], v[168:171], v[184:187], v[60:63]
	v_mfma_f32_16x16x32_bf16 v[56:59], v[176:179], v[184:187], v[56:59]
	v_mfma_f32_16x16x32_bf16 v[44:47], v[168:171], v[194:197], v[44:47]
	v_mfma_f32_16x16x32_bf16 v[40:43], v[176:179], v[194:197], v[40:43]
	v_mfma_f32_16x16x32_bf16 v[28:31], v[168:171], v[202:205], v[28:31]
	v_mfma_f32_16x16x32_bf16 v[24:27], v[176:179], v[202:205], v[24:27]
	v_mfma_f32_16x16x32_bf16 v[12:15], v[168:171], v[210:213], v[12:15]
	v_mfma_f32_16x16x32_bf16 v[8:11], v[176:179], v[210:213], v[8:11]
	s_setprio 0
	s_barrier
	s_add_i32 s58, 0, 0x18000
	v_add_u32_e32 v147, s58, v141
	s_add_i32 s59, 0, 0x1c000
	ds_read_b128 v[148:151], v147
	ds_read_b128 v[152:155], v147 offset:1024
	ds_read_b128 v[156:159], v147 offset:2048
	ds_read_b128 v[160:163], v147 offset:3072
	v_add_u32_e32 v147, s59, v141
	ds_read_b128 v[164:167], v147
	ds_read_b128 v[168:171], v147 offset:1024
	ds_read_b128 v[172:175], v147 offset:2048
	ds_read_b128 v[176:179], v147 offset:3072
	s_add_u32 s34, s34, 0x40000
	s_addc_u32 s35, s35, 0
	s_mov_b32 m0, s40
	v_lshl_add_u64 v[220:221], s[34:35], 0, v[128:129]
	ds_read_b128 v[180:183], v145 offset:32768
	ds_read_b128 v[184:187], v145 offset:33792
	ds_read_b128 v[190:193], v145 offset:34816
	ds_read_b128 v[194:197], v145 offset:35840
	ds_read_b128 v[198:201], v145 offset:36864
	ds_read_b128 v[202:205], v145 offset:37888
	ds_read_b128 v[206:209], v145 offset:38912
	ds_read_b128 v[210:213], v145 offset:39936
	global_load_lds_dwordx4 v[220:221], off
	v_lshl_add_u64 v[220:221], s[34:35], 0, v[130:131]
	s_mov_b32 m0, s41
	s_nop 0
	global_load_lds_dwordx4 v[220:221], off
	s_waitcnt vmcnt(8)
	s_waitcnt lgkmcnt(0)
	s_barrier
	s_setprio 1
	s_waitcnt lgkmcnt(0)
	v_mfma_f32_16x16x32_bf16 v[116:119], v[148:151], v[180:183], v[116:119]
	v_mfma_f32_16x16x32_bf16 v[112:115], v[156:159], v[180:183], v[112:115]
	v_mfma_f32_16x16x32_bf16 v[100:103], v[148:151], v[190:193], v[100:103]
	v_mfma_f32_16x16x32_bf16 v[96:99], v[156:159], v[190:193], v[96:99]
	v_mfma_f32_16x16x32_bf16 v[84:87], v[148:151], v[198:201], v[84:87]
	v_mfma_f32_16x16x32_bf16 v[80:83], v[156:159], v[198:201], v[80:83]
	v_mfma_f32_16x16x32_bf16 v[68:71], v[148:151], v[206:209], v[68:71]
	v_mfma_f32_16x16x32_bf16 v[64:67], v[156:159], v[206:209], v[64:67]
	v_mfma_f32_16x16x32_bf16 v[116:119], v[152:155], v[184:187], v[116:119]
	v_mfma_f32_16x16x32_bf16 v[112:115], v[160:163], v[184:187], v[112:115]
	v_mfma_f32_16x16x32_bf16 v[100:103], v[152:155], v[194:197], v[100:103]
	v_mfma_f32_16x16x32_bf16 v[96:99], v[160:163], v[194:197], v[96:99]
	v_mfma_f32_16x16x32_bf16 v[84:87], v[152:155], v[202:205], v[84:87]
	v_mfma_f32_16x16x32_bf16 v[80:83], v[160:163], v[202:205], v[80:83]
	v_mfma_f32_16x16x32_bf16 v[68:71], v[152:155], v[210:213], v[68:71]
	v_mfma_f32_16x16x32_bf16 v[64:67], v[160:163], v[210:213], v[64:67]
	s_setprio 0
	s_setprio 1
	v_mfma_f32_16x16x32_bf16 v[124:127], v[164:167], v[180:183], v[124:127]
	v_mfma_f32_16x16x32_bf16 v[120:123], v[172:175], v[180:183], v[120:123]
	v_mfma_f32_16x16x32_bf16 v[108:111], v[164:167], v[190:193], v[108:111]
	v_mfma_f32_16x16x32_bf16 v[104:107], v[172:175], v[190:193], v[104:107]
	v_mfma_f32_16x16x32_bf16 v[92:95], v[164:167], v[198:201], v[92:95]
	v_mfma_f32_16x16x32_bf16 v[88:91], v[172:175], v[198:201], v[88:91]
	v_mfma_f32_16x16x32_bf16 v[76:79], v[164:167], v[206:209], v[76:79]
	v_mfma_f32_16x16x32_bf16 v[72:75], v[172:175], v[206:209], v[72:75]
	v_mfma_f32_16x16x32_bf16 v[124:127], v[168:171], v[184:187], v[124:127]
	v_mfma_f32_16x16x32_bf16 v[120:123], v[176:179], v[184:187], v[120:123]
	v_mfma_f32_16x16x32_bf16 v[108:111], v[168:171], v[194:197], v[108:111]
	v_mfma_f32_16x16x32_bf16 v[104:107], v[176:179], v[194:197], v[104:107]
	v_mfma_f32_16x16x32_bf16 v[92:95], v[168:171], v[202:205], v[92:95]
	v_mfma_f32_16x16x32_bf16 v[88:91], v[176:179], v[202:205], v[88:91]
	v_mfma_f32_16x16x32_bf16 v[76:79], v[168:171], v[210:213], v[76:79]
	v_mfma_f32_16x16x32_bf16 v[72:75], v[176:179], v[210:213], v[72:75]
	s_setprio 0
	s_barrier
	s_add_i32 s34, s58, s33
	v_lshl_add_u64 v[138:139], v[138:139], 0, s[12:13]
	s_mov_b32 m0, s34
	ds_read_b128 v[180:183], v145 offset:49152
	ds_read_b128 v[184:187], v145 offset:50176
	ds_read_b128 v[190:193], v145 offset:51200
	ds_read_b128 v[194:197], v145 offset:52224
	ds_read_b128 v[198:201], v145 offset:53248
	ds_read_b128 v[202:205], v145 offset:54272
	ds_read_b128 v[206:209], v145 offset:55296
	ds_read_b128 v[210:213], v145 offset:56320
	global_load_lds_dwordx4 v[138:139], off
	s_add_i32 m0, s34, 0x2000
	s_add_u32 s4, s4, 0x40080
	v_lshl_add_u64 v[138:139], v[214:215], 0, s[12:13]
	s_addc_u32 s5, s5, 0
	s_add_i32 s34, s59, s33
	global_load_lds_dwordx4 v[138:139], off
	v_lshl_add_u64 v[138:139], s[4:5], 0, v[128:129]
	s_mov_b32 m0, s34
	s_nop 0
	global_load_lds_dwordx4 v[138:139], off
	v_lshl_add_u64 v[138:139], s[4:5], 0, v[130:131]
	s_add_i32 m0, s34, 0x2000
	s_nop 0
	global_load_lds_dwordx4 v[138:139], off
	v_lshl_add_u64 v[138:139], v[216:217], 0, s[12:13]
	s_mov_b32 m0, s43
	s_nop 0
	global_load_lds_dwordx4 v[138:139], off
	v_lshl_add_u64 v[138:139], v[218:219], 0, s[12:13]
	s_mov_b32 m0, s44
	s_nop 0
	global_load_lds_dwordx4 v[138:139], off
	s_waitcnt vmcnt(8)
	s_waitcnt lgkmcnt(0)
	s_barrier
	s_setprio 1
	s_waitcnt lgkmcnt(0)
	v_mfma_f32_16x16x32_bf16 v[52:55], v[148:151], v[180:183], v[52:55]
	v_mfma_f32_16x16x32_bf16 v[48:51], v[156:159], v[180:183], v[48:51]
	v_mfma_f32_16x16x32_bf16 v[36:39], v[148:151], v[190:193], v[36:39]
	v_mfma_f32_16x16x32_bf16 v[32:35], v[156:159], v[190:193], v[32:35]
	v_mfma_f32_16x16x32_bf16 v[20:23], v[148:151], v[198:201], v[20:23]
	v_mfma_f32_16x16x32_bf16 v[16:19], v[156:159], v[198:201], v[16:19]
	v_mfma_f32_16x16x32_bf16 v[4:7], v[148:151], v[206:209], v[4:7]
	v_mfma_f32_16x16x32_bf16 v[0:3], v[156:159], v[206:209], v[0:3]
	v_mfma_f32_16x16x32_bf16 v[52:55], v[152:155], v[184:187], v[52:55]
	v_mfma_f32_16x16x32_bf16 v[48:51], v[160:163], v[184:187], v[48:51]
	v_mfma_f32_16x16x32_bf16 v[36:39], v[152:155], v[194:197], v[36:39]
	v_mfma_f32_16x16x32_bf16 v[32:35], v[160:163], v[194:197], v[32:35]
	v_mfma_f32_16x16x32_bf16 v[20:23], v[152:155], v[202:205], v[20:23]
	v_mfma_f32_16x16x32_bf16 v[16:19], v[160:163], v[202:205], v[16:19]
	v_mfma_f32_16x16x32_bf16 v[4:7], v[152:155], v[210:213], v[4:7]
	v_mfma_f32_16x16x32_bf16 v[0:3], v[160:163], v[210:213], v[0:3]
	s_setprio 0
	s_setprio 1
	v_mfma_f32_16x16x32_bf16 v[60:63], v[164:167], v[180:183], v[60:63]
	v_mfma_f32_16x16x32_bf16 v[56:59], v[172:175], v[180:183], v[56:59]
	v_mfma_f32_16x16x32_bf16 v[44:47], v[164:167], v[190:193], v[44:47]
	v_mfma_f32_16x16x32_bf16 v[40:43], v[172:175], v[190:193], v[40:43]
	v_mfma_f32_16x16x32_bf16 v[28:31], v[164:167], v[198:201], v[28:31]
	v_mfma_f32_16x16x32_bf16 v[24:27], v[172:175], v[198:201], v[24:27]
	v_mfma_f32_16x16x32_bf16 v[12:15], v[164:167], v[206:209], v[12:15]
	v_mfma_f32_16x16x32_bf16 v[8:11], v[172:175], v[206:209], v[8:11]
	v_mfma_f32_16x16x32_bf16 v[60:63], v[168:171], v[184:187], v[60:63]
	v_mfma_f32_16x16x32_bf16 v[56:59], v[176:179], v[184:187], v[56:59]
	v_mfma_f32_16x16x32_bf16 v[44:47], v[168:171], v[194:197], v[44:47]
	v_mfma_f32_16x16x32_bf16 v[40:43], v[176:179], v[194:197], v[40:43]
	v_mfma_f32_16x16x32_bf16 v[28:31], v[168:171], v[202:205], v[28:31]
	v_mfma_f32_16x16x32_bf16 v[24:27], v[176:179], v[202:205], v[24:27]
	v_mfma_f32_16x16x32_bf16 v[12:15], v[168:171], v[210:213], v[12:15]
	v_mfma_f32_16x16x32_bf16 v[8:11], v[176:179], v[210:213], v[8:11]
	s_setprio 0
	s_barrier
	s_add_u32 s30, s30, 0x100
	s_addc_u32 s31, s31, 0
	s_add_u32 s19, s19, 0x100
	s_addc_u32 s21, s21, 0
	s_cmp_ge_i32 s57, s42
	s_mov_b32 s4, s57
	s_cbranch_scc0 .LBB0_1464
	s_branch .LBB0_1465
.Lpz_zero_4:
	v_mov_b64_e32 v[118:119], 0
	v_mov_b64_e32 v[116:117], 0
	v_mov_b64_e32 v[114:115], 0
	v_mov_b64_e32 v[112:113], 0
	v_mov_b64_e32 v[102:103], 0
	v_mov_b64_e32 v[100:101], 0
	v_mov_b64_e32 v[98:99], 0
	v_mov_b64_e32 v[96:97], 0
	v_mov_b64_e32 v[86:87], 0
	v_mov_b64_e32 v[84:85], 0
	v_mov_b64_e32 v[82:83], 0
	v_mov_b64_e32 v[80:81], 0
	v_mov_b64_e32 v[70:71], 0
	v_mov_b64_e32 v[68:69], 0
	v_mov_b64_e32 v[66:67], 0
	v_mov_b64_e32 v[64:65], 0
	v_mov_b64_e32 v[126:127], 0
	v_mov_b64_e32 v[124:125], 0
	v_mov_b64_e32 v[122:123], 0
	v_mov_b64_e32 v[120:121], 0
	v_mov_b64_e32 v[110:111], 0
	v_mov_b64_e32 v[108:109], 0
	v_mov_b64_e32 v[106:107], 0
	v_mov_b64_e32 v[104:105], 0
	v_mov_b64_e32 v[94:95], 0
	v_mov_b64_e32 v[92:93], 0
	v_mov_b64_e32 v[90:91], 0
	v_mov_b64_e32 v[88:89], 0
	v_mov_b64_e32 v[78:79], 0
	v_mov_b64_e32 v[76:77], 0
	v_mov_b64_e32 v[74:75], 0
	v_mov_b64_e32 v[72:73], 0
	v_mov_b64_e32 v[54:55], 0
	v_mov_b64_e32 v[52:53], 0
	v_mov_b64_e32 v[50:51], 0
	v_mov_b64_e32 v[48:49], 0
	v_mov_b64_e32 v[38:39], 0
	v_mov_b64_e32 v[36:37], 0
	v_mov_b64_e32 v[34:35], 0
	v_mov_b64_e32 v[32:33], 0
	v_mov_b64_e32 v[22:23], 0
	v_mov_b64_e32 v[20:21], 0
	v_mov_b64_e32 v[18:19], 0
	v_mov_b64_e32 v[16:17], 0
	v_mov_b64_e32 v[6:7], 0
	v_mov_b64_e32 v[4:5], 0
	v_mov_b64_e32 v[2:3], 0
	v_mov_b64_e32 v[0:1], 0
	v_mov_b64_e32 v[62:63], 0
	v_mov_b64_e32 v[60:61], 0
	v_mov_b64_e32 v[58:59], 0
	v_mov_b64_e32 v[56:57], 0
	v_mov_b64_e32 v[46:47], 0
	v_mov_b64_e32 v[44:45], 0
	v_mov_b64_e32 v[42:43], 0
	v_mov_b64_e32 v[40:41], 0
	v_mov_b64_e32 v[30:31], 0
	v_mov_b64_e32 v[28:29], 0
	v_mov_b64_e32 v[26:27], 0
	v_mov_b64_e32 v[24:25], 0
	v_mov_b64_e32 v[14:15], 0
	v_mov_b64_e32 v[12:13], 0
	v_mov_b64_e32 v[10:11], 0
	v_mov_b64_e32 v[8:9], 0
	s_branch .LBB0_1465

.LBB0_1550:
	s_andn2_b64 vcc, exec, s[18:19]
	s_waitcnt lgkmcnt(0)
	s_waitcnt vmcnt(0)
	s_cbranch_vccnz .Lpz_zero_5
	s_add_u32 s26, s26, 0xb0080
	s_addc_u32 s27, s27, 0
	s_add_u32 s56, s4, 0x100
	s_addc_u32 s57, s5, 0
	s_mov_b32 s4, 0
	ds_read_b128 v[138:141], v145
	ds_read_b128 v[150:153], v145 offset:1024
	ds_read_b128 v[154:157], v145 offset:2048
	ds_read_b128 v[158:161], v145 offset:3072
	ds_read_b128 v[162:165], v146
	ds_read_b128 v[166:169], v146 offset:1024
	ds_read_b128 v[170:173], v146 offset:2048
	ds_read_b128 v[174:177], v146 offset:3072
	s_add_i32 s58, s4, 2
	s_add_u32 s5, s26, 0xfff50080
	s_addc_u32 s28, s27, -1
	s_cmp_eq_u32 s44, s4
	s_cselect_b32 s4, s24, s56
	s_cselect_b32 s29, s23, s28
	s_cselect_b32 s28, s22, s5
	s_cselect_b32 s5, s25, s57
	v_lshl_add_u64 v[186:187], s[26:27], 0, v[132:133]
	s_add_i32 m0, s36, 0xc000
	ds_read_b128 v[178:181], v147
	ds_read_b128 v[182:185], v147 offset:1024
	ds_read_b128 v[190:193], v147 offset:2048
	ds_read_b128 v[194:197], v147 offset:3072
	ds_read_b128 v[198:201], v147 offset:4096
	ds_read_b128 v[202:205], v147 offset:5120
	ds_read_b128 v[206:209], v147 offset:6144
	ds_read_b128 v[210:213], v147 offset:7168
	global_load_lds_dwordx4 v[186:187], off
	v_lshl_add_u64 v[186:187], s[26:27], 0, v[134:135]
	s_add_i32 m0, s36, 0xe000
	s_nop 0
	global_load_lds_dwordx4 v[186:187], off
	s_waitcnt vmcnt(8)
	s_waitcnt lgkmcnt(0)
	s_barrier
	s_setprio 1
	s_waitcnt lgkmcnt(0)
	v_mfma_f32_16x16x32_bf16 v[120:123], v[138:141], v[178:181], 0
	v_mfma_f32_16x16x32_bf16 v[124:127], v[154:157], v[178:181], 0
	v_mfma_f32_16x16x32_bf16 v[108:111], v[138:141], v[190:193], 0
	v_mfma_f32_16x16x32_bf16 v[104:107], v[154:157], v[190:193], 0
	v_mfma_f32_16x16x32_bf16 v[92:95], v[138:141], v[198:201], 0
	v_mfma_f32_16x16x32_bf16 v[88:91], v[154:157], v[198:201], 0
	v_mfma_f32_16x16x32_bf16 v[76:79], v[138:141], v[206:209], 0
	v_mfma_f32_16x16x32_bf16 v[72:75], v[154:157], v[206:209], 0
	v_mfma_f32_16x16x32_bf16 v[120:123], v[150:153], v[182:185], v[120:123]
	v_mfma_f32_16x16x32_bf16 v[124:127], v[158:161], v[182:185], v[124:127]
	v_mfma_f32_16x16x32_bf16 v[108:111], v[150:153], v[194:197], v[108:111]
	v_mfma_f32_16x16x32_bf16 v[104:107], v[158:161], v[194:197], v[104:107]
	v_mfma_f32_16x16x32_bf16 v[92:95], v[150:153], v[202:205], v[92:95]
	v_mfma_f32_16x16x32_bf16 v[88:91], v[158:161], v[202:205], v[88:91]
	v_mfma_f32_16x16x32_bf16 v[76:79], v[150:153], v[210:213], v[76:79]
	v_mfma_f32_16x16x32_bf16 v[72:75], v[158:161], v[210:213], v[72:75]
	s_setprio 0
	s_setprio 1
	v_mfma_f32_16x16x32_bf16 v[116:119], v[162:165], v[178:181], 0
	v_mfma_f32_16x16x32_bf16 v[112:115], v[170:173], v[178:181], 0
	v_mfma_f32_16x16x32_bf16 v[100:103], v[162:165], v[190:193], 0
	v_mfma_f32_16x16x32_bf16 v[96:99], v[170:173], v[190:193], 0
	v_mfma_f32_16x16x32_bf16 v[84:87], v[162:165], v[198:201], 0
	v_mfma_f32_16x16x32_bf16 v[80:83], v[170:173], v[198:201], 0
	v_mfma_f32_16x16x32_bf16 v[68:71], v[162:165], v[206:209], 0
	v_mfma_f32_16x16x32_bf16 v[64:67], v[170:173], v[206:209], 0
	v_mfma_f32_16x16x32_bf16 v[116:119], v[166:169], v[182:185], v[116:119]
	v_mfma_f32_16x16x32_bf16 v[112:115], v[174:177], v[182:185], v[112:115]
	v_mfma_f32_16x16x32_bf16 v[100:103], v[166:169], v[194:197], v[100:103]
	v_mfma_f32_16x16x32_bf16 v[96:99], v[174:177], v[194:197], v[96:99]
	v_mfma_f32_16x16x32_bf16 v[84:87], v[166:169], v[202:205], v[84:87]
	v_mfma_f32_16x16x32_bf16 v[80:83], v[174:177], v[202:205], v[80:83]
	v_mfma_f32_16x16x32_bf16 v[68:71], v[166:169], v[210:213], v[68:71]
	v_mfma_f32_16x16x32_bf16 v[64:67], v[174:177], v[210:213], v[64:67]
	s_setprio 0
	s_barrier
	s_add_i32 s59, s49, s35
	v_lshl_add_u64 v[186:187], s[4:5], 0, v[128:129]
	s_mov_b32 m0, s59
	ds_read_b128 v[178:181], v147 offset:16384
	ds_read_b128 v[182:185], v147 offset:17408
	ds_read_b128 v[190:193], v147 offset:18432
	ds_read_b128 v[194:197], v147 offset:19456
	ds_read_b128 v[198:201], v147 offset:20480
	ds_read_b128 v[202:205], v147 offset:21504
	ds_read_b128 v[206:209], v147 offset:22528
	ds_read_b128 v[210:213], v147 offset:23552
	global_load_lds_dwordx4 v[186:187], off
	s_add_i32 m0, s59, 0x2000
	s_add_u32 s60, s4, 0xb0000
	v_lshl_add_u64 v[214:215], s[4:5], 0, v[130:131]
	s_addc_u32 s61, s5, 0
	s_add_i32 s59, s50, s35
	global_load_lds_dwordx4 v[214:215], off
	v_lshl_add_u64 v[216:217], s[60:61], 0, v[128:129]
	s_mov_b32 m0, s59
	v_lshl_add_u64 v[218:219], s[28:29], 0, v[130:131]
	global_load_lds_dwordx4 v[216:217], off
	v_lshl_add_u64 v[216:217], s[60:61], 0, v[130:131]
	s_add_i32 m0, s59, 0x2000
	s_nop 0
	global_load_lds_dwordx4 v[216:217], off
	v_lshl_add_u64 v[216:217], s[28:29], 0, v[128:129]
	s_mov_b32 m0, s36
	s_nop 0
	global_load_lds_dwordx4 v[216:217], off
	s_mov_b32 m0, s37
	s_nop 0
	global_load_lds_dwordx4 v[218:219], off
	s_waitcnt vmcnt(8)
	s_waitcnt lgkmcnt(0)
	s_barrier
	s_setprio 1
	s_waitcnt lgkmcnt(0)
	v_mfma_f32_16x16x32_bf16 v[60:63], v[138:141], v[178:181], 0
	v_mfma_f32_16x16x32_bf16 v[56:59], v[154:157], v[178:181], 0
	v_mfma_f32_16x16x32_bf16 v[44:47], v[138:141], v[190:193], 0
	v_mfma_f32_16x16x32_bf16 v[40:43], v[154:157], v[190:193], 0
	v_mfma_f32_16x16x32_bf16 v[28:31], v[138:141], v[198:201], 0
	v_mfma_f32_16x16x32_bf16 v[24:27], v[154:157], v[198:201], 0
	v_mfma_f32_16x16x32_bf16 v[12:15], v[138:141], v[206:209], 0
	v_mfma_f32_16x16x32_bf16 v[8:11], v[154:157], v[206:209], 0
	v_mfma_f32_16x16x32_bf16 v[60:63], v[150:153], v[182:185], v[60:63]
	v_mfma_f32_16x16x32_bf16 v[56:59], v[158:161], v[182:185], v[56:59]
	v_mfma_f32_16x16x32_bf16 v[44:47], v[150:153], v[194:197], v[44:47]
	v_mfma_f32_16x16x32_bf16 v[40:43], v[158:161], v[194:197], v[40:43]
	v_mfma_f32_16x16x32_bf16 v[28:31], v[150:153], v[202:205], v[28:31]
	v_mfma_f32_16x16x32_bf16 v[24:27], v[158:161], v[202:205], v[24:27]
	v_mfma_f32_16x16x32_bf16 v[12:15], v[150:153], v[210:213], v[12:15]
	v_mfma_f32_16x16x32_bf16 v[8:11], v[158:161], v[210:213], v[8:11]
	s_setprio 0
	s_setprio 1
	v_mfma_f32_16x16x32_bf16 v[52:55], v[162:165], v[178:181], 0
	v_mfma_f32_16x16x32_bf16 v[48:51], v[170:173], v[178:181], 0
	v_mfma_f32_16x16x32_bf16 v[36:39], v[162:165], v[190:193], 0
	v_mfma_f32_16x16x32_bf16 v[32:35], v[170:173], v[190:193], 0
	v_mfma_f32_16x16x32_bf16 v[20:23], v[162:165], v[198:201], 0
	v_mfma_f32_16x16x32_bf16 v[16:19], v[170:173], v[198:201], 0
	v_mfma_f32_16x16x32_bf16 v[4:7], v[162:165], v[206:209], 0
	v_mfma_f32_16x16x32_bf16 v[0:3], v[170:173], v[206:209], 0
	v_mfma_f32_16x16x32_bf16 v[52:55], v[166:169], v[182:185], v[52:55]
	v_mfma_f32_16x16x32_bf16 v[48:51], v[174:177], v[182:185], v[48:51]
	v_mfma_f32_16x16x32_bf16 v[36:39], v[166:169], v[194:197], v[36:39]
	v_mfma_f32_16x16x32_bf16 v[32:35], v[174:177], v[194:197], v[32:35]
	v_mfma_f32_16x16x32_bf16 v[20:23], v[166:169], v[202:205], v[20:23]
	v_mfma_f32_16x16x32_bf16 v[16:19], v[174:177], v[202:205], v[16:19]
	v_mfma_f32_16x16x32_bf16 v[4:7], v[166:169], v[210:213], v[4:7]
	v_mfma_f32_16x16x32_bf16 v[0:3], v[174:177], v[210:213], v[0:3]
	s_setprio 0
	s_barrier
	s_add_i32 s59, 0, 0x18000
	v_add_u32_e32 v149, s59, v143
	s_add_i32 s60, 0, 0x1c000
	ds_read_b128 v[138:141], v149
	ds_read_b128 v[150:153], v149 offset:1024
	ds_read_b128 v[154:157], v149 offset:2048
	ds_read_b128 v[158:161], v149 offset:3072
	v_add_u32_e32 v149, s60, v143
	ds_read_b128 v[162:165], v149
	ds_read_b128 v[166:169], v149 offset:1024
	ds_read_b128 v[170:173], v149 offset:2048
	ds_read_b128 v[174:177], v149 offset:3072
	s_add_u32 s28, s28, 0xb0000
	s_addc_u32 s29, s29, 0
	s_mov_b32 m0, s38
	v_lshl_add_u64 v[220:221], s[28:29], 0, v[128:129]
	ds_read_b128 v[178:181], v147 offset:32768
	ds_read_b128 v[182:185], v147 offset:33792
	ds_read_b128 v[190:193], v147 offset:34816
	ds_read_b128 v[194:197], v147 offset:35840
	ds_read_b128 v[198:201], v147 offset:36864
	ds_read_b128 v[202:205], v147 offset:37888
	ds_read_b128 v[206:209], v147 offset:38912
	ds_read_b128 v[210:213], v147 offset:39936
	global_load_lds_dwordx4 v[220:221], off
	v_lshl_add_u64 v[220:221], s[28:29], 0, v[130:131]
	s_mov_b32 m0, s39
	s_nop 0
	global_load_lds_dwordx4 v[220:221], off
	s_waitcnt vmcnt(8)
	s_waitcnt lgkmcnt(0)
	s_barrier
	s_setprio 1
	s_waitcnt lgkmcnt(0)
	v_mfma_f32_16x16x32_bf16 v[120:123], v[138:141], v[178:181], v[120:123]
	v_mfma_f32_16x16x32_bf16 v[124:127], v[154:157], v[178:181], v[124:127]
	v_mfma_f32_16x16x32_bf16 v[108:111], v[138:141], v[190:193], v[108:111]
	v_mfma_f32_16x16x32_bf16 v[104:107], v[154:157], v[190:193], v[104:107]
	v_mfma_f32_16x16x32_bf16 v[92:95], v[138:141], v[198:201], v[92:95]
	v_mfma_f32_16x16x32_bf16 v[88:91], v[154:157], v[198:201], v[88:91]
	v_mfma_f32_16x16x32_bf16 v[76:79], v[138:141], v[206:209], v[76:79]
	v_mfma_f32_16x16x32_bf16 v[72:75], v[154:157], v[206:209], v[72:75]
	v_mfma_f32_16x16x32_bf16 v[120:123], v[150:153], v[182:185], v[120:123]
	v_mfma_f32_16x16x32_bf16 v[124:127], v[158:161], v[182:185], v[124:127]
	v_mfma_f32_16x16x32_bf16 v[108:111], v[150:153], v[194:197], v[108:111]
	v_mfma_f32_16x16x32_bf16 v[104:107], v[158:161], v[194:197], v[104:107]
	v_mfma_f32_16x16x32_bf16 v[92:95], v[150:153], v[202:205], v[92:95]
	v_mfma_f32_16x16x32_bf16 v[88:91], v[158:161], v[202:205], v[88:91]
	v_mfma_f32_16x16x32_bf16 v[76:79], v[150:153], v[210:213], v[76:79]
	v_mfma_f32_16x16x32_bf16 v[72:75], v[158:161], v[210:213], v[72:75]
	s_setprio 0
	s_setprio 1
	v_mfma_f32_16x16x32_bf16 v[116:119], v[162:165], v[178:181], v[116:119]
	v_mfma_f32_16x16x32_bf16 v[112:115], v[170:173], v[178:181], v[112:115]
	v_mfma_f32_16x16x32_bf16 v[100:103], v[162:165], v[190:193], v[100:103]
	v_mfma_f32_16x16x32_bf16 v[96:99], v[170:173], v[190:193], v[96:99]
	v_mfma_f32_16x16x32_bf16 v[84:87], v[162:165], v[198:201], v[84:87]
	v_mfma_f32_16x16x32_bf16 v[80:83], v[170:173], v[198:201], v[80:83]
	v_mfma_f32_16x16x32_bf16 v[68:71], v[162:165], v[206:209], v[68:71]
	v_mfma_f32_16x16x32_bf16 v[64:67], v[170:173], v[206:209], v[64:67]
	v_mfma_f32_16x16x32_bf16 v[116:119], v[166:169], v[182:185], v[116:119]
	v_mfma_f32_16x16x32_bf16 v[112:115], v[174:177], v[182:185], v[112:115]
	v_mfma_f32_16x16x32_bf16 v[100:103], v[166:169], v[194:197], v[100:103]
	v_mfma_f32_16x16x32_bf16 v[96:99], v[174:177], v[194:197], v[96:99]
	v_mfma_f32_16x16x32_bf16 v[84:87], v[166:169], v[202:205], v[84:87]
	v_mfma_f32_16x16x32_bf16 v[80:83], v[174:177], v[202:205], v[80:83]
	v_mfma_f32_16x16x32_bf16 v[68:71], v[166:169], v[210:213], v[68:71]
	v_mfma_f32_16x16x32_bf16 v[64:67], v[174:177], v[210:213], v[64:67]
	s_setprio 0
	s_barrier
	s_add_i32 s28, s59, s35
	v_lshl_add_u64 v[186:187], v[186:187], 0, s[16:17]
	s_mov_b32 m0, s28
	ds_read_b128 v[178:181], v147 offset:49152
	ds_read_b128 v[182:185], v147 offset:50176
	ds_read_b128 v[190:193], v147 offset:51200
	ds_read_b128 v[194:197], v147 offset:52224
	ds_read_b128 v[198:201], v147 offset:53248
	ds_read_b128 v[202:205], v147 offset:54272
	ds_read_b128 v[206:209], v147 offset:55296
	ds_read_b128 v[210:213], v147 offset:56320
	global_load_lds_dwordx4 v[186:187], off
	s_add_i32 m0, s28, 0x2000
	s_add_u32 s4, s4, 0xb0080
	v_lshl_add_u64 v[186:187], v[214:215], 0, s[16:17]
	s_addc_u32 s5, s5, 0
	s_add_i32 s28, s60, s35
	global_load_lds_dwordx4 v[186:187], off
	v_lshl_add_u64 v[186:187], s[4:5], 0, v[128:129]
	s_mov_b32 m0, s28
	s_nop 0
	global_load_lds_dwordx4 v[186:187], off
	v_lshl_add_u64 v[186:187], s[4:5], 0, v[130:131]
	s_add_i32 m0, s28, 0x2000
	s_nop 0
	global_load_lds_dwordx4 v[186:187], off
	v_lshl_add_u64 v[186:187], v[216:217], 0, s[16:17]
	s_mov_b32 m0, s42
	s_nop 0
	global_load_lds_dwordx4 v[186:187], off
	v_lshl_add_u64 v[186:187], v[218:219], 0, s[16:17]
	s_mov_b32 m0, s43
	s_nop 0
	global_load_lds_dwordx4 v[186:187], off
	s_waitcnt vmcnt(8)
	s_waitcnt lgkmcnt(0)
	s_barrier
	s_setprio 1
	s_waitcnt lgkmcnt(0)
	v_mfma_f32_16x16x32_bf16 v[60:63], v[138:141], v[178:181], v[60:63]
	v_mfma_f32_16x16x32_bf16 v[56:59], v[154:157], v[178:181], v[56:59]
	v_mfma_f32_16x16x32_bf16 v[44:47], v[138:141], v[190:193], v[44:47]
	v_mfma_f32_16x16x32_bf16 v[40:43], v[154:157], v[190:193], v[40:43]
	v_mfma_f32_16x16x32_bf16 v[28:31], v[138:141], v[198:201], v[28:31]
	v_mfma_f32_16x16x32_bf16 v[24:27], v[154:157], v[198:201], v[24:27]
	v_mfma_f32_16x16x32_bf16 v[12:15], v[138:141], v[206:209], v[12:15]
	v_mfma_f32_16x16x32_bf16 v[8:11], v[154:157], v[206:209], v[8:11]
	v_mfma_f32_16x16x32_bf16 v[60:63], v[150:153], v[182:185], v[60:63]
	v_mfma_f32_16x16x32_bf16 v[56:59], v[158:161], v[182:185], v[56:59]
	v_mfma_f32_16x16x32_bf16 v[44:47], v[150:153], v[194:197], v[44:47]
	v_mfma_f32_16x16x32_bf16 v[40:43], v[158:161], v[194:197], v[40:43]
	v_mfma_f32_16x16x32_bf16 v[28:31], v[150:153], v[202:205], v[28:31]
	v_mfma_f32_16x16x32_bf16 v[24:27], v[158:161], v[202:205], v[24:27]
	v_mfma_f32_16x16x32_bf16 v[12:15], v[150:153], v[210:213], v[12:15]
	v_mfma_f32_16x16x32_bf16 v[8:11], v[158:161], v[210:213], v[8:11]
	s_setprio 0
	s_setprio 1
	v_mfma_f32_16x16x32_bf16 v[52:55], v[162:165], v[178:181], v[52:55]
	v_mfma_f32_16x16x32_bf16 v[48:51], v[170:173], v[178:181], v[48:51]
	v_mfma_f32_16x16x32_bf16 v[36:39], v[162:165], v[190:193], v[36:39]
	v_mfma_f32_16x16x32_bf16 v[32:35], v[170:173], v[190:193], v[32:35]
	v_mfma_f32_16x16x32_bf16 v[20:23], v[162:165], v[198:201], v[20:23]
	v_mfma_f32_16x16x32_bf16 v[16:19], v[170:173], v[198:201], v[16:19]
	v_mfma_f32_16x16x32_bf16 v[4:7], v[162:165], v[206:209], v[4:7]
	v_mfma_f32_16x16x32_bf16 v[0:3], v[170:173], v[206:209], v[0:3]
	v_mfma_f32_16x16x32_bf16 v[52:55], v[166:169], v[182:185], v[52:55]
	v_mfma_f32_16x16x32_bf16 v[48:51], v[174:177], v[182:185], v[48:51]
	v_mfma_f32_16x16x32_bf16 v[36:39], v[166:169], v[194:197], v[36:39]
	v_mfma_f32_16x16x32_bf16 v[32:35], v[174:177], v[194:197], v[32:35]
	v_mfma_f32_16x16x32_bf16 v[20:23], v[166:169], v[202:205], v[20:23]
	v_mfma_f32_16x16x32_bf16 v[16:19], v[174:177], v[202:205], v[16:19]
	v_mfma_f32_16x16x32_bf16 v[4:7], v[166:169], v[210:213], v[4:7]
	v_mfma_f32_16x16x32_bf16 v[0:3], v[174:177], v[210:213], v[0:3]
	s_setprio 0
	s_barrier
	s_add_u32 s26, s26, 0x100
	s_addc_u32 s27, s27, 0
	s_add_u32 s56, s56, 0x100
	s_addc_u32 s57, s57, 0
	s_cmp_ge_i32 s58, s41
	s_mov_b32 s4, s58
	s_cbranch_scc0 .LBB0_1552
	s_branch .LBB0_1553

.LBB0_1652:
	s_andn2_b64 vcc, exec, s[12:13]
	s_cbranch_vccnz .Lpz_zero_6
	s_add_u32 s28, s28, 0x40080
	s_addc_u32 s29, s29, 0
	s_add_u32 s17, s30, 0x100
	s_addc_u32 s19, s31, 0
	s_mov_b32 s30, 0
	ds_read_b128 v[138:141], v147
	ds_read_b128 v[152:155], v147 offset:1024
	ds_read_b128 v[156:159], v147 offset:2048
	ds_read_b128 v[160:163], v147 offset:3072
	ds_read_b128 v[164:167], v148
	ds_read_b128 v[168:171], v148 offset:1024
	ds_read_b128 v[172:175], v148 offset:2048
	ds_read_b128 v[176:179], v148 offset:3072
	s_add_i32 s53, s30, 2
	s_add_u32 s31, s28, 0xfffc0080
	s_addc_u32 s34, s29, -1
	s_cmp_eq_u32 s44, s30
	s_cselect_b32 s30, s22, s17
	s_cselect_b32 s35, s21, s34
	s_cselect_b32 s34, s20, s31
	s_cselect_b32 s31, s23, s19
	v_lshl_add_u64 v[142:143], s[28:29], 0, v[132:133]
	s_add_i32 m0, s27, 0xc000
	ds_read_b128 v[180:183], v149
	ds_read_b128 v[184:187], v149 offset:1024
	ds_read_b128 v[188:191], v149 offset:2048
	ds_read_b128 v[192:195], v149 offset:3072
	ds_read_b128 v[196:199], v149 offset:4096
	ds_read_b128 v[200:203], v149 offset:5120
	ds_read_b128 v[204:207], v149 offset:6144
	ds_read_b128 v[208:211], v149 offset:7168
	global_load_lds_dwordx4 v[142:143], off
	v_lshl_add_u64 v[142:143], s[28:29], 0, v[134:135]
	s_add_i32 m0, s27, 0xe000
	s_nop 0
	global_load_lds_dwordx4 v[142:143], off
	s_waitcnt vmcnt(8)
	s_waitcnt lgkmcnt(0)
	s_barrier
	s_setprio 1
	s_waitcnt lgkmcnt(0)
	v_mfma_f32_16x16x32_bf16 v[124:127], v[138:141], v[180:183], 0
	v_mfma_f32_16x16x32_bf16 v[120:123], v[156:159], v[180:183], 0
	v_mfma_f32_16x16x32_bf16 v[108:111], v[138:141], v[188:191], 0
	v_mfma_f32_16x16x32_bf16 v[104:107], v[156:159], v[188:191], 0
	v_mfma_f32_16x16x32_bf16 v[92:95], v[138:141], v[196:199], 0
	v_mfma_f32_16x16x32_bf16 v[88:91], v[156:159], v[196:199], 0
	v_mfma_f32_16x16x32_bf16 v[76:79], v[138:141], v[204:207], 0
	v_mfma_f32_16x16x32_bf16 v[72:75], v[156:159], v[204:207], 0
	v_mfma_f32_16x16x32_bf16 v[124:127], v[152:155], v[184:187], v[124:127]
	v_mfma_f32_16x16x32_bf16 v[120:123], v[160:163], v[184:187], v[120:123]
	v_mfma_f32_16x16x32_bf16 v[108:111], v[152:155], v[192:195], v[108:111]
	v_mfma_f32_16x16x32_bf16 v[104:107], v[160:163], v[192:195], v[104:107]
	v_mfma_f32_16x16x32_bf16 v[92:95], v[152:155], v[200:203], v[92:95]
	v_mfma_f32_16x16x32_bf16 v[88:91], v[160:163], v[200:203], v[88:91]
	v_mfma_f32_16x16x32_bf16 v[76:79], v[152:155], v[208:211], v[76:79]
	v_mfma_f32_16x16x32_bf16 v[72:75], v[160:163], v[208:211], v[72:75]
	s_setprio 0
	s_setprio 1
	v_mfma_f32_16x16x32_bf16 v[116:119], v[164:167], v[180:183], 0
	v_mfma_f32_16x16x32_bf16 v[112:115], v[172:175], v[180:183], 0
	v_mfma_f32_16x16x32_bf16 v[100:103], v[164:167], v[188:191], 0
	v_mfma_f32_16x16x32_bf16 v[96:99], v[172:175], v[188:191], 0
	v_mfma_f32_16x16x32_bf16 v[84:87], v[164:167], v[196:199], 0
	v_mfma_f32_16x16x32_bf16 v[80:83], v[172:175], v[196:199], 0
	v_mfma_f32_16x16x32_bf16 v[68:71], v[164:167], v[204:207], 0
	v_mfma_f32_16x16x32_bf16 v[64:67], v[172:175], v[204:207], 0
	v_mfma_f32_16x16x32_bf16 v[116:119], v[168:171], v[184:187], v[116:119]
	v_mfma_f32_16x16x32_bf16 v[112:115], v[176:179], v[184:187], v[112:115]
	v_mfma_f32_16x16x32_bf16 v[100:103], v[168:171], v[192:195], v[100:103]
	v_mfma_f32_16x16x32_bf16 v[96:99], v[176:179], v[192:195], v[96:99]
	v_mfma_f32_16x16x32_bf16 v[84:87], v[168:171], v[200:203], v[84:87]
	v_mfma_f32_16x16x32_bf16 v[80:83], v[176:179], v[200:203], v[80:83]
	v_mfma_f32_16x16x32_bf16 v[68:71], v[168:171], v[208:211], v[68:71]
	v_mfma_f32_16x16x32_bf16 v[64:67], v[176:179], v[208:211], v[64:67]
	s_setprio 0
	s_barrier
	s_add_i32 s54, s49, s33
	v_lshl_add_u64 v[142:143], s[30:31], 0, v[128:129]
	s_mov_b32 m0, s54
	ds_read_b128 v[180:183], v149 offset:16384
	ds_read_b128 v[184:187], v149 offset:17408
	ds_read_b128 v[188:191], v149 offset:18432
	ds_read_b128 v[192:195], v149 offset:19456
	ds_read_b128 v[196:199], v149 offset:20480
	ds_read_b128 v[200:203], v149 offset:21504
	ds_read_b128 v[204:207], v149 offset:22528
	ds_read_b128 v[208:211], v149 offset:23552
	global_load_lds_dwordx4 v[142:143], off
	s_add_i32 m0, s54, 0x2000
	s_add_u32 s54, s30, 0x40000
	v_lshl_add_u64 v[212:213], s[30:31], 0, v[130:131]
	s_addc_u32 s55, s31, 0
	s_add_i32 s56, s50, s33
	global_load_lds_dwordx4 v[212:213], off
	v_lshl_add_u64 v[214:215], s[54:55], 0, v[128:129]
	s_mov_b32 m0, s56
	v_lshl_add_u64 v[216:217], s[34:35], 0, v[130:131]
	global_load_lds_dwordx4 v[214:215], off
	v_lshl_add_u64 v[214:215], s[54:55], 0, v[130:131]
	s_add_i32 m0, s56, 0x2000
	s_nop 0
	global_load_lds_dwordx4 v[214:215], off
	v_lshl_add_u64 v[214:215], s[34:35], 0, v[128:129]
	s_mov_b32 m0, s27
	s_nop 0
	global_load_lds_dwordx4 v[214:215], off
	s_mov_b32 m0, s38
	s_nop 0
	global_load_lds_dwordx4 v[216:217], off
	s_waitcnt vmcnt(8)
	s_waitcnt lgkmcnt(0)
	s_barrier
	s_setprio 1
	s_waitcnt lgkmcnt(0)
	v_mfma_f32_16x16x32_bf16 v[60:63], v[138:141], v[180:183], 0
	v_mfma_f32_16x16x32_bf16 v[56:59], v[156:159], v[180:183], 0
	v_mfma_f32_16x16x32_bf16 v[44:47], v[138:141], v[188:191], 0
	v_mfma_f32_16x16x32_bf16 v[40:43], v[156:159], v[188:191], 0
	v_mfma_f32_16x16x32_bf16 v[28:31], v[138:141], v[196:199], 0
	v_mfma_f32_16x16x32_bf16 v[24:27], v[156:159], v[196:199], 0
	v_mfma_f32_16x16x32_bf16 v[12:15], v[138:141], v[204:207], 0
	v_mfma_f32_16x16x32_bf16 v[8:11], v[156:159], v[204:207], 0
	v_mfma_f32_16x16x32_bf16 v[60:63], v[152:155], v[184:187], v[60:63]
	v_mfma_f32_16x16x32_bf16 v[56:59], v[160:163], v[184:187], v[56:59]
	v_mfma_f32_16x16x32_bf16 v[44:47], v[152:155], v[192:195], v[44:47]
	v_mfma_f32_16x16x32_bf16 v[40:43], v[160:163], v[192:195], v[40:43]
	v_mfma_f32_16x16x32_bf16 v[28:31], v[152:155], v[200:203], v[28:31]
	v_mfma_f32_16x16x32_bf16 v[24:27], v[160:163], v[200:203], v[24:27]
	v_mfma_f32_16x16x32_bf16 v[12:15], v[152:155], v[208:211], v[12:15]
	v_mfma_f32_16x16x32_bf16 v[8:11], v[160:163], v[208:211], v[8:11]
	s_setprio 0
	s_setprio 1
	v_mfma_f32_16x16x32_bf16 v[52:55], v[164:167], v[180:183], 0
	v_mfma_f32_16x16x32_bf16 v[48:51], v[172:175], v[180:183], 0
	v_mfma_f32_16x16x32_bf16 v[36:39], v[164:167], v[188:191], 0
	v_mfma_f32_16x16x32_bf16 v[32:35], v[172:175], v[188:191], 0
	v_mfma_f32_16x16x32_bf16 v[20:23], v[164:167], v[196:199], 0
	v_mfma_f32_16x16x32_bf16 v[16:19], v[172:175], v[196:199], 0
	v_mfma_f32_16x16x32_bf16 v[4:7], v[164:167], v[204:207], 0
	v_mfma_f32_16x16x32_bf16 v[0:3], v[172:175], v[204:207], 0
	v_mfma_f32_16x16x32_bf16 v[52:55], v[168:171], v[184:187], v[52:55]
	v_mfma_f32_16x16x32_bf16 v[48:51], v[176:179], v[184:187], v[48:51]
	v_mfma_f32_16x16x32_bf16 v[36:39], v[168:171], v[192:195], v[36:39]
	v_mfma_f32_16x16x32_bf16 v[32:35], v[176:179], v[192:195], v[32:35]
	v_mfma_f32_16x16x32_bf16 v[20:23], v[168:171], v[200:203], v[20:23]
	v_mfma_f32_16x16x32_bf16 v[16:19], v[176:179], v[200:203], v[16:19]
	v_mfma_f32_16x16x32_bf16 v[4:7], v[168:171], v[208:211], v[4:7]
	v_mfma_f32_16x16x32_bf16 v[0:3], v[176:179], v[208:211], v[0:3]
	s_setprio 0
	s_barrier
	s_add_i32 s54, 0, 0x18000
	v_add_u32_e32 v151, s54, v145
	s_add_i32 s55, 0, 0x1c000
	ds_read_b128 v[138:141], v151
	ds_read_b128 v[152:155], v151 offset:1024
	ds_read_b128 v[156:159], v151 offset:2048
	ds_read_b128 v[160:163], v151 offset:3072
	v_add_u32_e32 v151, s55, v145
	ds_read_b128 v[164:167], v151
	ds_read_b128 v[168:171], v151 offset:1024
	ds_read_b128 v[172:175], v151 offset:2048
	ds_read_b128 v[176:179], v151 offset:3072
	s_add_u32 s34, s34, 0x40000
	s_addc_u32 s35, s35, 0
	s_mov_b32 m0, s39
	v_lshl_add_u64 v[218:219], s[34:35], 0, v[128:129]
	ds_read_b128 v[180:183], v149 offset:32768
	ds_read_b128 v[184:187], v149 offset:33792
	ds_read_b128 v[188:191], v149 offset:34816
	ds_read_b128 v[192:195], v149 offset:35840
	ds_read_b128 v[196:199], v149 offset:36864
	ds_read_b128 v[200:203], v149 offset:37888
	ds_read_b128 v[204:207], v149 offset:38912
	ds_read_b128 v[208:211], v149 offset:39936
	global_load_lds_dwordx4 v[218:219], off
	v_lshl_add_u64 v[218:219], s[34:35], 0, v[130:131]
	s_mov_b32 m0, s40
	s_nop 0
	global_load_lds_dwordx4 v[218:219], off
	s_waitcnt vmcnt(8)
	s_waitcnt lgkmcnt(0)
	s_barrier
	s_setprio 1
	s_waitcnt lgkmcnt(0)
	v_mfma_f32_16x16x32_bf16 v[124:127], v[138:141], v[180:183], v[124:127]
	v_mfma_f32_16x16x32_bf16 v[120:123], v[156:159], v[180:183], v[120:123]
	v_mfma_f32_16x16x32_bf16 v[108:111], v[138:141], v[188:191], v[108:111]
	v_mfma_f32_16x16x32_bf16 v[104:107], v[156:159], v[188:191], v[104:107]
	v_mfma_f32_16x16x32_bf16 v[92:95], v[138:141], v[196:199], v[92:95]
	v_mfma_f32_16x16x32_bf16 v[88:91], v[156:159], v[196:199], v[88:91]
	v_mfma_f32_16x16x32_bf16 v[76:79], v[138:141], v[204:207], v[76:79]
	v_mfma_f32_16x16x32_bf16 v[72:75], v[156:159], v[204:207], v[72:75]
	v_mfma_f32_16x16x32_bf16 v[124:127], v[152:155], v[184:187], v[124:127]
	v_mfma_f32_16x16x32_bf16 v[120:123], v[160:163], v[184:187], v[120:123]
	v_mfma_f32_16x16x32_bf16 v[108:111], v[152:155], v[192:195], v[108:111]
	v_mfma_f32_16x16x32_bf16 v[104:107], v[160:163], v[192:195], v[104:107]
	v_mfma_f32_16x16x32_bf16 v[92:95], v[152:155], v[200:203], v[92:95]
	v_mfma_f32_16x16x32_bf16 v[88:91], v[160:163], v[200:203], v[88:91]
	v_mfma_f32_16x16x32_bf16 v[76:79], v[152:155], v[208:211], v[76:79]
	v_mfma_f32_16x16x32_bf16 v[72:75], v[160:163], v[208:211], v[72:75]
	s_setprio 0
	s_setprio 1
	v_mfma_f32_16x16x32_bf16 v[116:119], v[164:167], v[180:183], v[116:119]
	v_mfma_f32_16x16x32_bf16 v[112:115], v[172:175], v[180:183], v[112:115]
	v_mfma_f32_16x16x32_bf16 v[100:103], v[164:167], v[188:191], v[100:103]
	v_mfma_f32_16x16x32_bf16 v[96:99], v[172:175], v[188:191], v[96:99]
	v_mfma_f32_16x16x32_bf16 v[84:87], v[164:167], v[196:199], v[84:87]
	v_mfma_f32_16x16x32_bf16 v[80:83], v[172:175], v[196:199], v[80:83]
	v_mfma_f32_16x16x32_bf16 v[68:71], v[164:167], v[204:207], v[68:71]
	v_mfma_f32_16x16x32_bf16 v[64:67], v[172:175], v[204:207], v[64:67]
	v_mfma_f32_16x16x32_bf16 v[116:119], v[168:171], v[184:187], v[116:119]
	v_mfma_f32_16x16x32_bf16 v[112:115], v[176:179], v[184:187], v[112:115]
	v_mfma_f32_16x16x32_bf16 v[100:103], v[168:171], v[192:195], v[100:103]
	v_mfma_f32_16x16x32_bf16 v[96:99], v[176:179], v[192:195], v[96:99]
	v_mfma_f32_16x16x32_bf16 v[84:87], v[168:171], v[200:203], v[84:87]
	v_mfma_f32_16x16x32_bf16 v[80:83], v[176:179], v[200:203], v[80:83]
	v_mfma_f32_16x16x32_bf16 v[68:71], v[168:171], v[208:211], v[68:71]
	v_mfma_f32_16x16x32_bf16 v[64:67], v[176:179], v[208:211], v[64:67]
	s_setprio 0
	s_barrier
	s_add_i32 s34, s54, s33
	v_lshl_add_u64 v[142:143], v[142:143], 0, s[10:11]
	s_mov_b32 m0, s34
	ds_read_b128 v[180:183], v149 offset:49152
	ds_read_b128 v[184:187], v149 offset:50176
	ds_read_b128 v[188:191], v149 offset:51200
	ds_read_b128 v[192:195], v149 offset:52224
	ds_read_b128 v[196:199], v149 offset:53248
	ds_read_b128 v[200:203], v149 offset:54272
	ds_read_b128 v[204:207], v149 offset:55296
	ds_read_b128 v[208:211], v149 offset:56320
	global_load_lds_dwordx4 v[142:143], off
	s_add_i32 m0, s34, 0x2000
	s_add_u32 s30, s30, 0x40080
	v_lshl_add_u64 v[142:143], v[212:213], 0, s[10:11]
	s_addc_u32 s31, s31, 0
	s_add_i32 s34, s55, s33
	global_load_lds_dwordx4 v[142:143], off
	v_lshl_add_u64 v[142:143], s[30:31], 0, v[128:129]
	s_mov_b32 m0, s34
	s_nop 0
	global_load_lds_dwordx4 v[142:143], off
	v_lshl_add_u64 v[142:143], s[30:31], 0, v[130:131]
	s_add_i32 m0, s34, 0x2000
	s_nop 0
	global_load_lds_dwordx4 v[142:143], off
	v_lshl_add_u64 v[142:143], v[214:215], 0, s[10:11]
	s_mov_b32 m0, s42
	s_nop 0
	global_load_lds_dwordx4 v[142:143], off
	v_lshl_add_u64 v[142:143], v[216:217], 0, s[10:11]
	s_mov_b32 m0, s43
	s_nop 0
	global_load_lds_dwordx4 v[142:143], off
	s_waitcnt vmcnt(8)
	s_waitcnt lgkmcnt(0)
	s_barrier
	s_setprio 1
	s_waitcnt lgkmcnt(0)
	v_mfma_f32_16x16x32_bf16 v[60:63], v[138:141], v[180:183], v[60:63]
	v_mfma_f32_16x16x32_bf16 v[56:59], v[156:159], v[180:183], v[56:59]
	v_mfma_f32_16x16x32_bf16 v[44:47], v[138:141], v[188:191], v[44:47]
	v_mfma_f32_16x16x32_bf16 v[40:43], v[156:159], v[188:191], v[40:43]
	v_mfma_f32_16x16x32_bf16 v[28:31], v[138:141], v[196:199], v[28:31]
	v_mfma_f32_16x16x32_bf16 v[24:27], v[156:159], v[196:199], v[24:27]
	v_mfma_f32_16x16x32_bf16 v[12:15], v[138:141], v[204:207], v[12:15]
	v_mfma_f32_16x16x32_bf16 v[8:11], v[156:159], v[204:207], v[8:11]
	v_mfma_f32_16x16x32_bf16 v[60:63], v[152:155], v[184:187], v[60:63]
	v_mfma_f32_16x16x32_bf16 v[56:59], v[160:163], v[184:187], v[56:59]
	v_mfma_f32_16x16x32_bf16 v[44:47], v[152:155], v[192:195], v[44:47]
	v_mfma_f32_16x16x32_bf16 v[40:43], v[160:163], v[192:195], v[40:43]
	v_mfma_f32_16x16x32_bf16 v[28:31], v[152:155], v[200:203], v[28:31]
	v_mfma_f32_16x16x32_bf16 v[24:27], v[160:163], v[200:203], v[24:27]
	v_mfma_f32_16x16x32_bf16 v[12:15], v[152:155], v[208:211], v[12:15]
	v_mfma_f32_16x16x32_bf16 v[8:11], v[160:163], v[208:211], v[8:11]
	s_setprio 0
	s_setprio 1
	v_mfma_f32_16x16x32_bf16 v[52:55], v[164:167], v[180:183], v[52:55]
	v_mfma_f32_16x16x32_bf16 v[48:51], v[172:175], v[180:183], v[48:51]
	v_mfma_f32_16x16x32_bf16 v[36:39], v[164:167], v[188:191], v[36:39]
	v_mfma_f32_16x16x32_bf16 v[32:35], v[172:175], v[188:191], v[32:35]
	v_mfma_f32_16x16x32_bf16 v[20:23], v[164:167], v[196:199], v[20:23]
	v_mfma_f32_16x16x32_bf16 v[16:19], v[172:175], v[196:199], v[16:19]
	v_mfma_f32_16x16x32_bf16 v[4:7], v[164:167], v[204:207], v[4:7]
	v_mfma_f32_16x16x32_bf16 v[0:3], v[172:175], v[204:207], v[0:3]
	v_mfma_f32_16x16x32_bf16 v[52:55], v[168:171], v[184:187], v[52:55]
	v_mfma_f32_16x16x32_bf16 v[48:51], v[176:179], v[184:187], v[48:51]
	v_mfma_f32_16x16x32_bf16 v[36:39], v[168:171], v[192:195], v[36:39]
	v_mfma_f32_16x16x32_bf16 v[32:35], v[176:179], v[192:195], v[32:35]
	v_mfma_f32_16x16x32_bf16 v[20:23], v[168:171], v[200:203], v[20:23]
	v_mfma_f32_16x16x32_bf16 v[16:19], v[176:179], v[200:203], v[16:19]
	v_mfma_f32_16x16x32_bf16 v[4:7], v[168:171], v[208:211], v[4:7]
	v_mfma_f32_16x16x32_bf16 v[0:3], v[176:179], v[208:211], v[0:3]
	s_setprio 0
	s_barrier
	s_add_u32 s28, s28, 0x100
	s_addc_u32 s29, s29, 0
	s_add_u32 s17, s17, 0x100
	s_addc_u32 s19, s19, 0
	s_cmp_ge_i32 s53, s41
	s_mov_b32 s30, s53
	s_cbranch_scc0 .LBB0_1654
	s_branch .LBB0_1655
.Lpz_zero_6:
	v_mov_b64_e32 v[126:127], 0
	v_mov_b64_e32 v[124:125], 0
	v_mov_b64_e32 v[122:123], 0
	v_mov_b64_e32 v[120:121], 0
	v_mov_b64_e32 v[110:111], 0
	v_mov_b64_e32 v[108:109], 0
	v_mov_b64_e32 v[106:107], 0
	v_mov_b64_e32 v[104:105], 0
	v_mov_b64_e32 v[94:95], 0
	v_mov_b64_e32 v[92:93], 0
	v_mov_b64_e32 v[90:91], 0
	v_mov_b64_e32 v[88:89], 0
	v_mov_b64_e32 v[78:79], 0
	v_mov_b64_e32 v[76:77], 0
	v_mov_b64_e32 v[74:75], 0
	v_mov_b64_e32 v[72:73], 0
	v_mov_b64_e32 v[118:119], 0
	v_mov_b64_e32 v[116:117], 0
	v_mov_b64_e32 v[114:115], 0
	v_mov_b64_e32 v[112:113], 0
	v_mov_b64_e32 v[102:103], 0
	v_mov_b64_e32 v[100:101], 0
	v_mov_b64_e32 v[98:99], 0
	v_mov_b64_e32 v[96:97], 0
	v_mov_b64_e32 v[86:87], 0
	v_mov_b64_e32 v[84:85], 0
	v_mov_b64_e32 v[82:83], 0
	v_mov_b64_e32 v[80:81], 0
	v_mov_b64_e32 v[70:71], 0
	v_mov_b64_e32 v[68:69], 0
	v_mov_b64_e32 v[66:67], 0
	v_mov_b64_e32 v[64:65], 0
	v_mov_b64_e32 v[62:63], 0
	v_mov_b64_e32 v[60:61], 0
	v_mov_b64_e32 v[58:59], 0
	v_mov_b64_e32 v[56:57], 0
	v_mov_b64_e32 v[46:47], 0
	v_mov_b64_e32 v[44:45], 0
	v_mov_b64_e32 v[42:43], 0
	v_mov_b64_e32 v[40:41], 0
	v_mov_b64_e32 v[30:31], 0
	v_mov_b64_e32 v[28:29], 0
	v_mov_b64_e32 v[26:27], 0
	v_mov_b64_e32 v[24:25], 0
	v_mov_b64_e32 v[14:15], 0
	v_mov_b64_e32 v[12:13], 0
	v_mov_b64_e32 v[10:11], 0
	v_mov_b64_e32 v[8:9], 0
	v_mov_b64_e32 v[54:55], 0
	v_mov_b64_e32 v[52:53], 0
	v_mov_b64_e32 v[50:51], 0
	v_mov_b64_e32 v[48:49], 0
	v_mov_b64_e32 v[38:39], 0
	v_mov_b64_e32 v[36:37], 0
	v_mov_b64_e32 v[34:35], 0
	v_mov_b64_e32 v[32:33], 0
	v_mov_b64_e32 v[22:23], 0
	v_mov_b64_e32 v[20:21], 0
	v_mov_b64_e32 v[18:19], 0
	v_mov_b64_e32 v[16:17], 0
	v_mov_b64_e32 v[6:7], 0
	v_mov_b64_e32 v[4:5], 0
	v_mov_b64_e32 v[2:3], 0
	v_mov_b64_e32 v[0:1], 0
	s_branch .LBB0_1655
